# scan: batched transposing y reduction (2 DPP/step), next-chunk touch loads in loader waves
# speedup vs baseline: 1.0006x; 1.0006x over previous
; #define LAS __attribute__((address_space(3)))
; #define SCAN_LOAD(chn) SCAN_LOAD_RAW()
; __device__ __forceinline__ void phase_scan(const Params& p, LAS unsigned char* lds) {
;     ...
;                     { unsigned m1u_ = 0xBC00BC00u; asm volatile("" : "+s"(m1u_));
;                       typedef unsigned u32x4_ __attribute__((ext_vector_type(4))); const u32x4_ m1v_ = {m1u_, m1u_, m1u_, m1u_}; const h16x8 m1_ = __builtin_bit_cast(h16x8, m1v_);
;                       const h16x8 r8 = pr + mu_r8 * (pr * m1_ + qr_), k8 = pk + mu_k8 * (pk * m1_ + qk_), v8 = pv + mu_v8 * (pv * m1_ + qv_);
;                       const h16x8 w8 = pw + mu_w8 * (pw * m1_ + qw_), a8 = pa + mu_a8 * (pa * m1_ + qa_);
;                       h16x8 tw8;
; #pragma unroll
;                       for (int pi = 0; pi < 4; ++pi) { qr[pi] = (f32x2){(float)r8[2 * pi], (float)r8[2 * pi + 1]}; qk[pi] = (f32x2){(float)k8[2 * pi], (float)k8[2 * pi + 1]};
;                           qv[2 * pi] = (float)v8[2 * pi]; qv[2 * pi + 1] = (float)v8[2 * pi + 1];
;                           const f32x2 tx = (f32x2){(float)w8[2 * pi], (float)w8[2 * pi + 1]} * 2.8853900817779268f;
;                           const f32x2 dn = (f32x2){__builtin_amdgcn_exp2f(tx[0]), __builtin_amdgcn_exp2f(tx[1])} + 1.f;
;                           const f32x2 th = (f32x2){__builtin_amdgcn_rcpf(dn[0]), __builtin_amdgcn_rcpf(dn[1])} * -2.f + 1.f;
;                           tw8[2 * pi] = (h16)th[0]; tw8[2 * pi + 1] = (h16)th[1]; }
;                       *(LAS h16x8*)(TWp + s_sub * 72 + c8) = tw8; *(LAS h16x8*)(QAp + s_sub * 72 + c8) = a8; }
;                     if (cn + 1 < SEQ / 32) SCAN_LOAD(cn + 1);
.LBB0_604:
	s_cmp_eq_u64 s[0:1], 0
	s_cbranch_scc1 .Lscan_wave_top
	s_waitcnt vmcnt(9)
	v_mov_b64_e32 v[94:95], v[102:103]
	s_waitcnt vmcnt(8)
	v_mov_b64_e32 v[86:87], v[106:107]
	s_waitcnt vmcnt(7)
	v_mov_b64_e32 v[78:79], v[110:111]
	s_waitcnt vmcnt(4)
	v_mov_b64_e32 v[98:99], v[114:115]
	s_waitcnt vmcnt(3)
	v_mov_b64_e32 v[90:91], v[118:119]
	s_waitcnt vmcnt(2)
	v_mov_b64_e32 v[82:83], v[122:123]
	v_mov_b64_e32 v[96:97], v[104:105]
	v_mov_b64_e32 v[88:89], v[108:109]
	v_mov_b64_e32 v[80:81], v[112:113]
	v_mov_b64_e32 v[100:101], v[116:117]
	v_mov_b64_e32 v[92:93], v[120:121]
	v_mov_b64_e32 v[84:85], v[124:125]
	s_and_saveexec_b64 s[14:15], s[0:1]
	s_xor_b64 s[54:55], exec, s[14:15]
	s_cbranch_execz .LBB0_617
	s_cmpk_eq_i32 s81, 0xff
	s_cbranch_scc1 .LBB0_608
	s_mov_b32 s14, 0xbc00bc00
	s_cmpk_eq_i32 s81, 0xfe
	s_waitcnt vmcnt(1)
	v_pk_fma_f16 v0, v4, s14, v12
	v_pk_fma_f16 v102, v5, s14, v13
	v_pk_fma_f16 v103, v6, s14, v14
	v_pk_fma_f16 v104, v7, s14, v15
	v_pk_fma_f16 v107, v74, v103, v6
	v_pk_fma_f16 v109, v75, v104, v7
	v_pk_fma_f16 v105, v65, v102, v5
	v_pk_fma_f16 v0, v64, v0, v4
	v_cvt_f32_f16_e32 v104, v105
	v_cvt_f32_f16_e32 v102, v0
	v_cvt_f32_f16_sdwa v103, v0 dst_sel:DWORD dst_unused:UNUSED_PAD src0_sel:WORD_1
	v_cvt_f32_f16_sdwa v105, v105 dst_sel:DWORD dst_unused:UNUSED_PAD src0_sel:WORD_1
	v_cvt_f32_f16_e32 v106, v107
	v_cvt_f32_f16_sdwa v107, v107 dst_sel:DWORD dst_unused:UNUSED_PAD src0_sel:WORD_1
	v_cvt_f32_f16_e32 v108, v109
	v_cvt_f32_f16_sdwa v109, v109 dst_sel:DWORD dst_unused:UNUSED_PAD src0_sel:WORD_1
	v_pk_mul_f32 v[102:103], v[102:103], s[30:31] op_sel_hi:[1,0]
	v_pk_mul_f32 v[104:105], v[104:105], s[30:31] op_sel_hi:[1,0]
	v_pk_mul_f32 v[106:107], v[106:107], s[30:31] op_sel_hi:[1,0]
	v_pk_mul_f32 v[108:109], v[108:109], s[30:31] op_sel_hi:[1,0]
	v_exp_f32_e32 v102, v102
	v_exp_f32_e32 v103, v103
	v_exp_f32_e32 v104, v104
	v_exp_f32_e32 v105, v105
	v_exp_f32_e32 v106, v106
	v_exp_f32_e32 v107, v107
	v_exp_f32_e32 v108, v108
	v_exp_f32_e32 v109, v109
	v_pk_add_f32 v[102:103], v[102:103], 1.0 op_sel_hi:[1,0]
	v_pk_add_f32 v[104:105], v[104:105], 1.0 op_sel_hi:[1,0]
	v_pk_add_f32 v[106:107], v[106:107], 1.0 op_sel_hi:[1,0]
	v_pk_add_f32 v[108:109], v[108:109], 1.0 op_sel_hi:[1,0]
	v_rcp_f32_e32 v102, v102
	v_rcp_f32_e32 v103, v103
	v_rcp_f32_e32 v104, v104
	v_rcp_f32_e32 v105, v105
	v_rcp_f32_e32 v106, v106
	v_rcp_f32_e32 v107, v107
	v_rcp_f32_e32 v108, v108
	v_rcp_f32_e32 v109, v109
	s_waitcnt vmcnt(0)
	v_pk_fma_f16 v112, v8, s14, v16
	v_pk_fma_f16 v113, v9, s14, v17
	v_pk_fma_f16 v114, v10, s14, v18
	v_pk_fma_f16 v0, v11, s14, v19
	v_pk_fma_f32 v[110:111], v[102:103], 2.0, 1.0 op_sel_hi:[1,0,0] neg_lo:[1,0,0] neg_hi:[1,0,0]
	v_pk_fma_f32 v[102:103], v[104:105], 2.0, 1.0 op_sel_hi:[1,0,0] neg_lo:[1,0,0] neg_hi:[1,0,0]
	v_pk_fma_f32 v[106:107], v[106:107], 2.0, 1.0 op_sel_hi:[1,0,0] neg_lo:[1,0,0] neg_hi:[1,0,0]
	v_pk_fma_f32 v[104:105], v[108:109], 2.0, 1.0 op_sel_hi:[1,0,0] neg_lo:[1,0,0] neg_hi:[1,0,0]
	v_cvt_pk_f16_f32 v103, v102, v103
	v_cvt_pk_f16_f32 v105, v104, v105
	v_cvt_pk_f16_f32 v104, v106, v107
	v_cvt_pk_f16_f32 v102, v110, v111
	v_pk_fma_f16 v109, v77, v0, v11
	v_pk_fma_f16 v108, v76, v114, v10
	v_pk_fma_f16 v107, v67, v113, v9
	v_pk_fma_f16 v106, v66, v112, v8
	ds_write_b128 v171, v[102:105] offset:18432
	ds_write_b128 v172, v[106:109] offset:19584
	s_cbranch_scc1 .LBB0_609
	v_lshl_add_u64 v[4:5], v[148:149], 0, s[20:21]
	global_load_dwordx4 v[102:105], v[146:147], off
	global_load_dwordx4 v[106:109], v[146:147], off offset:2048
	global_load_dwordx4 v[110:113], v[4:5], off
	s_nop 0
	global_load_dwordx4 v[4:7], v[148:149], off offset:2048
	global_load_dwordx4 v[8:11], v[148:149], off offset:2176
	global_load_dwordx4 v[114:117], v[152:153], off
	global_load_dwordx4 v[118:121], v[152:153], off offset:2048
	v_lshl_add_u64 v[12:13], v[150:151], 0, s[20:21]
	global_load_dwordx4 v[122:125], v[12:13], off
	s_nop 0
	global_load_dwordx4 v[12:15], v[150:151], off offset:2048
	global_load_dwordx4 v[16:19], v[150:151], off offset:2176
	s_lshl_b64 s[34:35], s[46:47], 1
	v_lshl_add_u64 v[146:147], v[146:147], 0, s[34:35]
	v_lshl_add_u64 v[148:149], v[148:149], 0, s[34:35]
	s_lshl_b64 s[34:35], s[40:41], 1
	v_lshl_add_u64 v[152:153], v[146:147], 0, s[34:35]
	v_lshl_add_u64 v[150:151], v[148:149], 0, s[34:35]
	v_lshl_add_u64 v[252:253], v[148:149], 0, s[20:21]
	global_load_dword v255, v[146:147], off
	global_load_dword v255, v[146:147], off offset:2048
	global_load_dword v255, v[148:149], off offset:2048
	global_load_dword v255, v[148:149], off offset:2176
	global_load_dword v255, v[252:253], off
	s_branch .LBB0_610

; __device__ __forceinline__ void phase_scan(const Params& p, LAS unsigned char* lds) {
;     ...
;             if (wave < 4) {
;                 if (n >= 0) {
;                     __builtin_amdgcn_s_setprio(3);
;                     const LAS float* sR = OPS + (n & 1) * SET_F + j0; const LAS float* sW = sR + 2048; const LAS float* sK = sW + 2048; const LAS float* sA = sK + 2048; const LAS float* sB = sA + 2048; const LAS float* sV = OPS + (n & 1) * SET_F + 10240;
;                     LAS float* sY = sYb + (n & 1) * 512;
;                     f32x4 a_ = *(const LAS f32x4*)(sA), w_ = *(const LAS f32x4*)(sW), b_ = *(const LAS f32x4*)(sB);
;                     f32x4 k_ = *(const LAS f32x4*)(sK), r_ = *(const LAS f32x4*)(sR);
;                     f32x4 vq[4];
; #pragma unroll
;                     for (int u = 0; u < 4; ++u) vq[u] = *(const LAS f32x4*)(sV + srow * 32 + 4 * u);
;                     f32x4 rp = r_;
; #pragma unroll
;                     for (int hb = 0; hb < 2; ++hb) {
;                         f32x4 vn[4];
; #pragma unroll
;                         for (int u = 0; u < 4; ++u) vn[u] = *(const LAS f32x4*)(sV + srow * 32 + ((16 * (hb + 1)) & 31) + 4 * u);
; #pragma unroll
;                         for (int u16 = 0; u16 < 16; ++u16) {
;                             const int s = 16 * hb + u16;
;                             const int sn = (s + 1) & 31;
;                             const f32x4 a_n = *(const LAS f32x4*)(sA + sn * 64), w_n = *(const LAS f32x4*)(sW + sn * 64), b_n = *(const LAS f32x4*)(sB + sn * 64);
;                             const f32x4 k_n = *(const LAS f32x4*)(sK + sn * 64), r_n = *(const LAS f32x4*)(sR + sn * 64);
;                             const float v = vq[u16 >> 2][u16 & 3];
;                             const f32x2 vv = {v, v};
;                             f32x2 pp = S01 * (f32x2){a_[0], a_[1]}; pp = S23 * (f32x2){a_[2], a_[3]} + pp;
;                             f32x2 yy = S01 * (f32x2){rp[0], rp[1]}; yy = S23 * (f32x2){rp[2], rp[3]} + yy;
;                             float sa = pp[0] + pp[1], y = yy[0] + yy[1];
;                             sa += dpp_f<0xB1>(sa); y += dpp_f<0xB1>(y);
;                             sa += dpp_f<0x4E>(sa); y += dpp_f<0x4E>(y);
;                             sa += dpp_f<0x141>(sa); y += dpp_f<0x141>(y);
;                             sa += dpp_f<0x140>(sa); y += dpp_f<0x140>(y);
.Lscan_wave_top:
	s_mov_b64 s[54:55], 0
	s_cmp_lt_i32 s81, 0
	s_cbranch_scc1 .LBB0_603
	s_setprio 3
	s_and_b32 s14, s81, 1
	s_mul_i32 s15, s14, 0xa800
	s_add_i32 s34, s15, 0x8800
	v_add_u32_e32 v240, s15, v178
	v_add_u32_e32 v242, s34, v179
	v_add_u32_e32 v241, 0x8800, v240
	v_lshl_add_u32 v243, s14, 11, v184
	ds_read_b128 v[80:83], v241 offset:24576
	ds_read_b128 v[84:87], v240 offset:43008
	ds_read_b128 v[92:95], v240 offset:51200
	ds_read_b128 v[88:91], v241 offset:32768
	ds_read_b128 v[96:99], v240 offset:34816
	ds_read_b128 v[216:219], v242 offset:40960
	ds_read_b128 v[100:103], v241 offset:24832
	ds_read_b128 v[104:107], v240 offset:43264
	ds_read_b128 v[112:115], v240 offset:51456
	ds_read_b128 v[108:111], v241 offset:33024
	ds_read_b128 v[116:119], v240 offset:35072
	ds_read_b128 v[220:223], v242 offset:40976
	v_bfe_u32 v244, v130, 2, 2
	s_nop 0
	v_lshl_add_u32 v244, v244, 8, v243
	s_waitcnt lgkmcnt(7)
	v_pk_mul_f32 v[228:229], v[166:167], v[80:81]
	ds_read_b128 v[120:123], v241 offset:25088
	v_pk_fma_f32 v[228:229], v[164:165], v[82:83], v[228:229]
	ds_read_b128 v[124:127], v240 offset:43520
	v_add_f32_e32 v236, v228, v229
	s_waitcnt lgkmcnt(8)
	v_pk_mul_f32 v[232:233], v[216:217], v[92:93] op_sel_hi:[0,1]
	ds_read_b128 v[208:211], v240 offset:51712
	v_add_f32_dpp v236, v236, v236 quad_perm:[1,0,3,2] row_mask:0xf bank_mask:0xf bound_ctrl:1
	v_pk_mul_f32 v[234:235], v[216:217], v[94:95] op_sel_hi:[0,1]
	ds_read_b128 v[204:207], v241 offset:33280
	v_add_f32_dpp v236, v236, v236 quad_perm:[2,3,0,1] row_mask:0xf bank_mask:0xf bound_ctrl:1
	v_pk_fma_f32 v[166:167], v[166:167], v[84:85], v[232:233]
	ds_read_b128 v[212:215], v240 offset:35328
	v_add_f32_dpp v236, v236, v236 row_half_mirror row_mask:0xf bank_mask:0xf bound_ctrl:1
	v_pk_fma_f32 v[164:165], v[164:165], v[86:87], v[234:235]
	s_nop 0
	v_add_f32_dpp v236, v236, v236 row_mirror row_mask:0xf bank_mask:0xf bound_ctrl:1
	s_nop 0
	v_pk_fma_f32 v[166:167], v[88:89], v[236:237], v[166:167] op_sel_hi:[1,0,1]
	v_pk_fma_f32 v[164:165], v[90:91], v[236:237], v[164:165] op_sel_hi:[1,0,1]
	s_waitcnt lgkmcnt(6)
	v_pk_mul_f32 v[228:229], v[166:167], v[100:101]
	v_pk_mul_f32 v[230:231], v[166:167], v[96:97]
	v_pk_fma_f32 v[228:229], v[164:165], v[102:103], v[228:229]
	v_pk_fma_f32 v[230:231], v[164:165], v[98:99], v[230:231]
	v_add_f32_e32 v236, v228, v229
	v_pk_mul_f32 v[232:233], v[216:217], v[112:113] op_sel:[1,0]
	v_add_f32_e32 v245, v230, v231
	v_add_f32_dpp v236, v236, v236 quad_perm:[1,0,3,2] row_mask:0xf bank_mask:0xf bound_ctrl:1
	v_pk_mul_f32 v[234:235], v[216:217], v[114:115] op_sel:[1,0]
	ds_read_b128 v[80:83], v241 offset:25344
	v_add_f32_dpp v236, v236, v236 quad_perm:[2,3,0,1] row_mask:0xf bank_mask:0xf bound_ctrl:1
	v_pk_fma_f32 v[166:167], v[166:167], v[104:105], v[232:233]
	ds_read_b128 v[84:87], v240 offset:43776
	v_add_f32_dpp v236, v236, v236 row_half_mirror row_mask:0xf bank_mask:0xf bound_ctrl:1
	v_pk_fma_f32 v[164:165], v[164:165], v[106:107], v[234:235]
	ds_read_b128 v[92:95], v240 offset:51968
	v_add_f32_dpp v236, v236, v236 row_mirror row_mask:0xf bank_mask:0xf bound_ctrl:1
	ds_read_b128 v[88:91], v241 offset:33536
	ds_read_b128 v[96:99], v240 offset:35584
	v_pk_fma_f32 v[166:167], v[108:109], v[236:237], v[166:167] op_sel_hi:[1,0,1]
	v_pk_fma_f32 v[164:165], v[110:111], v[236:237], v[164:165] op_sel_hi:[1,0,1]
	ds_read_b128 v[224:227], v242 offset:40992
	s_waitcnt lgkmcnt(6)
	v_pk_mul_f32 v[228:229], v[166:167], v[120:121]
	v_pk_mul_f32 v[230:231], v[166:167], v[116:117]
	v_pk_fma_f32 v[228:229], v[164:165], v[122:123], v[228:229]
	v_pk_fma_f32 v[230:231], v[164:165], v[118:119], v[230:231]
	v_add_f32_e32 v236, v228, v229
	v_pk_mul_f32 v[232:233], v[218:219], v[208:209] op_sel_hi:[0,1]
	v_add_f32_e32 v246, v230, v231
	v_add_f32_dpp v236, v236, v236 quad_perm:[1,0,3,2] row_mask:0xf bank_mask:0xf bound_ctrl:1
	v_pk_mul_f32 v[234:235], v[218:219], v[210:211] op_sel_hi:[0,1]
	ds_read_b128 v[100:103], v241 offset:25600
	v_add_f32_dpp v236, v236, v236 quad_perm:[2,3,0,1] row_mask:0xf bank_mask:0xf bound_ctrl:1
	v_pk_fma_f32 v[166:167], v[166:167], v[124:125], v[232:233]
	ds_read_b128 v[104:107], v240 offset:44032
	v_add_f32_dpp v236, v236, v236 row_half_mirror row_mask:0xf bank_mask:0xf bound_ctrl:1
	v_pk_fma_f32 v[164:165], v[164:165], v[126:127], v[234:235]
	ds_read_b128 v[112:115], v240 offset:52224
	v_add_f32_dpp v236, v236, v236 row_mirror row_mask:0xf bank_mask:0xf bound_ctrl:1
	ds_read_b128 v[108:111], v241 offset:33792
	ds_read_b128 v[116:119], v240 offset:35840
	v_pk_fma_f32 v[166:167], v[204:205], v[236:237], v[166:167] op_sel_hi:[1,0,1]
	v_pk_fma_f32 v[164:165], v[206:207], v[236:237], v[164:165] op_sel_hi:[1,0,1]
	s_waitcnt lgkmcnt(6)
	v_pk_mul_f32 v[228:229], v[166:167], v[80:81]
	v_pk_mul_f32 v[230:231], v[166:167], v[212:213]
	v_pk_fma_f32 v[228:229], v[164:165], v[82:83], v[228:229]
	v_pk_fma_f32 v[230:231], v[164:165], v[214:215], v[230:231]
	v_add_f32_e32 v236, v228, v229
	v_pk_mul_f32 v[232:233], v[218:219], v[92:93] op_sel:[1,0]
	v_add_f32_e32 v247, v230, v231
	v_add_f32_dpp v236, v236, v236 quad_perm:[1,0,3,2] row_mask:0xf bank_mask:0xf bound_ctrl:1
	v_pk_mul_f32 v[234:235], v[218:219], v[94:95] op_sel:[1,0]
	ds_read_b128 v[120:123], v241 offset:25856
	v_add_f32_dpp v236, v236, v236 quad_perm:[2,3,0,1] row_mask:0xf bank_mask:0xf bound_ctrl:1
	v_pk_fma_f32 v[166:167], v[166:167], v[84:85], v[232:233]
	ds_read_b128 v[124:127], v240 offset:44288
	v_add_f32_dpp v236, v236, v236 row_half_mirror row_mask:0xf bank_mask:0xf bound_ctrl:1
	v_pk_fma_f32 v[164:165], v[164:165], v[86:87], v[234:235]
	ds_read_b128 v[208:211], v240 offset:52480
	v_add_f32_dpp v236, v236, v236 row_mirror row_mask:0xf bank_mask:0xf bound_ctrl:1
	ds_read_b128 v[204:207], v241 offset:34048
	ds_read_b128 v[212:215], v240 offset:36096
	v_pk_fma_f32 v[166:167], v[88:89], v[236:237], v[166:167] op_sel_hi:[1,0,1]
	v_pk_fma_f32 v[164:165], v[90:91], v[236:237], v[164:165] op_sel_hi:[1,0,1]
	s_waitcnt lgkmcnt(5)
; #define LAS __attribute__((address_space(3)))
; template <int CTRL> __device__ __forceinline__ float dpp_f(float x) { return __int_as_float(__builtin_amdgcn_update_dpp(0, __float_as_int(x), CTRL, 0xf, 0xf, false)); }
; __device__ __forceinline__ void phase_scan(const Params& p, LAS unsigned char* lds) {
;     ...
;                         for (int u16 = 0; u16 < 16; ++u16) {
;                             const int s = 16 * hb + u16;
;                             const int sn = (s + 1) & 31;
;                             const f32x4 a_n = *(const LAS f32x4*)(sA + sn * 64), w_n = *(const LAS f32x4*)(sW + sn * 64), b_n = *(const LAS f32x4*)(sB + sn * 64);
;                             const f32x4 k_n = *(const LAS f32x4*)(sK + sn * 64), r_n = *(const LAS f32x4*)(sR + sn * 64);
;                             const float v = vq[u16 >> 2][u16 & 3];
;                             const f32x2 vv = {v, v};
;                             f32x2 pp = S01 * (f32x2){a_[0], a_[1]}; pp = S23 * (f32x2){a_[2], a_[3]} + pp;
;                             f32x2 yy = S01 * (f32x2){rp[0], rp[1]}; yy = S23 * (f32x2){rp[2], rp[3]} + yy;
;                             float sa = pp[0] + pp[1], y = yy[0] + yy[1];
;                             sa += dpp_f<0xB1>(sa); y += dpp_f<0xB1>(y);
;                             sa += dpp_f<0x4E>(sa); y += dpp_f<0x4E>(y);
;                             sa += dpp_f<0x141>(sa); y += dpp_f<0x141>(y);
;                             sa += dpp_f<0x140>(sa); y += dpp_f<0x140>(y);
;                             sY[((s - 1) & 31) * 16 + srow] = y;
;                             const f32x2 sv = {sa, sa};
;                             S01 = S01 * (f32x2){w_[0], w_[1]} + vv * (f32x2){k_[0], k_[1]};
;                             S23 = S23 * (f32x2){w_[2], w_[3]} + vv * (f32x2){k_[2], k_[3]};
;                             S01 = sv * (f32x2){b_[0], b_[1]} + S01;
;                             S23 = sv * (f32x2){b_[2], b_[3]} + S23;
;                             rp = r_;
;                             a_ = a_n; w_ = w_n; b_ = b_n; k_ = k_n; r_ = r_n;
;                         }
	v_pk_mul_f32 v[228:229], v[166:167], v[100:101]
	v_pk_mul_f32 v[230:231], v[166:167], v[96:97]
	v_pk_fma_f32 v[228:229], v[164:165], v[102:103], v[228:229]
	v_pk_fma_f32 v[230:231], v[164:165], v[98:99], v[230:231]
	v_add_f32_e32 v236, v228, v229
	v_pk_mul_f32 v[232:233], v[220:221], v[112:113] op_sel_hi:[0,1]
	v_add_f32_e32 v248, v230, v231
	v_add_f32_dpp v236, v236, v236 quad_perm:[1,0,3,2] row_mask:0xf bank_mask:0xf bound_ctrl:1
	v_pk_mul_f32 v[234:235], v[220:221], v[114:115] op_sel_hi:[0,1]
	ds_read_b128 v[80:83], v241 offset:26112
	v_add_f32_dpp v236, v236, v236 quad_perm:[2,3,0,1] row_mask:0xf bank_mask:0xf bound_ctrl:1
	v_pk_fma_f32 v[166:167], v[166:167], v[104:105], v[232:233]
	ds_read_b128 v[84:87], v240 offset:44544
	v_add_f32_dpp v236, v236, v236 row_half_mirror row_mask:0xf bank_mask:0xf bound_ctrl:1
	v_pk_fma_f32 v[164:165], v[164:165], v[106:107], v[234:235]
	ds_read_b128 v[92:95], v240 offset:52736
	v_add_f32_dpp v236, v236, v236 row_mirror row_mask:0xf bank_mask:0xf bound_ctrl:1
	ds_read_b128 v[88:91], v241 offset:34304
	ds_read_b128 v[96:99], v240 offset:36352
	v_pk_fma_f32 v[166:167], v[108:109], v[236:237], v[166:167] op_sel_hi:[1,0,1]
	v_pk_fma_f32 v[164:165], v[110:111], v[236:237], v[164:165] op_sel_hi:[1,0,1]
	s_waitcnt lgkmcnt(5)
	v_pk_mul_f32 v[228:229], v[166:167], v[120:121]
	v_pk_mul_f32 v[230:231], v[166:167], v[116:117]
	v_pk_fma_f32 v[228:229], v[164:165], v[122:123], v[228:229]
	v_pk_fma_f32 v[230:231], v[164:165], v[118:119], v[230:231]
	v_add_f32_e32 v236, v228, v229
	v_pk_mul_f32 v[232:233], v[220:221], v[208:209] op_sel:[1,0]
	v_add_f32_e32 v249, v230, v231
	v_add_f32_dpp v236, v236, v236 quad_perm:[1,0,3,2] row_mask:0xf bank_mask:0xf bound_ctrl:1
	v_pk_mul_f32 v[234:235], v[220:221], v[210:211] op_sel:[1,0]
	ds_read_b128 v[100:103], v241 offset:26368
	v_add_f32_dpp v236, v236, v236 quad_perm:[2,3,0,1] row_mask:0xf bank_mask:0xf bound_ctrl:1
	v_pk_fma_f32 v[166:167], v[166:167], v[124:125], v[232:233]
	ds_read_b128 v[104:107], v240 offset:44800
	v_add_f32_dpp v236, v236, v236 row_half_mirror row_mask:0xf bank_mask:0xf bound_ctrl:1
	v_pk_fma_f32 v[164:165], v[164:165], v[126:127], v[234:235]
	ds_read_b128 v[112:115], v240 offset:52992
	v_add_f32_dpp v236, v236, v236 row_mirror row_mask:0xf bank_mask:0xf bound_ctrl:1
	ds_read_b128 v[108:111], v241 offset:34560
	ds_read_b128 v[116:119], v240 offset:36608
	v_pk_fma_f32 v[166:167], v[204:205], v[236:237], v[166:167] op_sel_hi:[1,0,1]
	v_pk_fma_f32 v[164:165], v[206:207], v[236:237], v[164:165] op_sel_hi:[1,0,1]
	ds_read_b128 v[216:219], v242 offset:41008
	s_waitcnt lgkmcnt(6)
	v_pk_mul_f32 v[228:229], v[166:167], v[80:81]
	v_pk_mul_f32 v[230:231], v[166:167], v[212:213]
	v_pk_fma_f32 v[228:229], v[164:165], v[82:83], v[228:229]
	v_pk_fma_f32 v[230:231], v[164:165], v[214:215], v[230:231]
	v_add_f32_e32 v236, v228, v229
	v_pk_mul_f32 v[232:233], v[222:223], v[92:93] op_sel_hi:[0,1]
	v_add_f32_e32 v250, v230, v231
	v_add_f32_dpp v236, v236, v236 quad_perm:[1,0,3,2] row_mask:0xf bank_mask:0xf bound_ctrl:1
	v_pk_mul_f32 v[234:235], v[222:223], v[94:95] op_sel_hi:[0,1]
	ds_read_b128 v[120:123], v241 offset:26624
	v_add_f32_dpp v236, v236, v236 quad_perm:[2,3,0,1] row_mask:0xf bank_mask:0xf bound_ctrl:1
	v_pk_fma_f32 v[166:167], v[166:167], v[84:85], v[232:233]
	ds_read_b128 v[124:127], v240 offset:45056
	v_add_f32_dpp v236, v236, v236 row_half_mirror row_mask:0xf bank_mask:0xf bound_ctrl:1
	v_pk_fma_f32 v[164:165], v[164:165], v[86:87], v[234:235]
	ds_read_b128 v[208:211], v240 offset:53248
	v_add_f32_dpp v236, v236, v236 row_mirror row_mask:0xf bank_mask:0xf bound_ctrl:1
	ds_read_b128 v[204:207], v241 offset:34816
	ds_read_b128 v[212:215], v240 offset:36864
	v_pk_fma_f32 v[166:167], v[88:89], v[236:237], v[166:167] op_sel_hi:[1,0,1]
	v_pk_fma_f32 v[164:165], v[90:91], v[236:237], v[164:165] op_sel_hi:[1,0,1]
	s_waitcnt lgkmcnt(6)
	v_pk_mul_f32 v[228:229], v[166:167], v[100:101]
	v_pk_mul_f32 v[230:231], v[166:167], v[96:97]
	v_pk_fma_f32 v[228:229], v[164:165], v[102:103], v[228:229]
	v_pk_fma_f32 v[230:231], v[164:165], v[98:99], v[230:231]
	v_add_f32_e32 v236, v228, v229
	v_pk_mul_f32 v[232:233], v[222:223], v[112:113] op_sel:[1,0]
	v_add_f32_e32 v251, v230, v231
	v_add_f32_dpp v236, v236, v236 quad_perm:[1,0,3,2] row_mask:0xf bank_mask:0xf bound_ctrl:1
	v_pk_mul_f32 v[234:235], v[222:223], v[114:115] op_sel:[1,0]
	ds_read_b128 v[80:83], v241 offset:26880
	v_add_f32_dpp v236, v236, v236 quad_perm:[2,3,0,1] row_mask:0xf bank_mask:0xf bound_ctrl:1
	v_pk_fma_f32 v[166:167], v[166:167], v[104:105], v[232:233]
	ds_read_b128 v[84:87], v240 offset:45312
	v_add_f32_dpp v236, v236, v236 row_half_mirror row_mask:0xf bank_mask:0xf bound_ctrl:1
	v_pk_fma_f32 v[164:165], v[164:165], v[106:107], v[234:235]
	ds_read_b128 v[92:95], v240 offset:53504
	v_add_f32_dpp v236, v236, v236 row_mirror row_mask:0xf bank_mask:0xf bound_ctrl:1
	ds_read_b128 v[88:91], v241 offset:35072
	ds_read_b128 v[96:99], v240 offset:37120
	v_pk_fma_f32 v[166:167], v[108:109], v[236:237], v[166:167] op_sel_hi:[1,0,1]
	v_pk_fma_f32 v[164:165], v[110:111], v[236:237], v[164:165] op_sel_hi:[1,0,1]
	s_waitcnt lgkmcnt(5)
; #define LAS __attribute__((address_space(3)))
; template <int CTRL> __device__ __forceinline__ float dpp_f(float x) { return __int_as_float(__builtin_amdgcn_update_dpp(0, __float_as_int(x), CTRL, 0xf, 0xf, false)); }
; __device__ __forceinline__ void phase_scan(const Params& p, LAS unsigned char* lds) {
;     ...
;                         for (int u16 = 0; u16 < 16; ++u16) {
;                             const int s = 16 * hb + u16;
;                             const int sn = (s + 1) & 31;
;                             const f32x4 a_n = *(const LAS f32x4*)(sA + sn * 64), w_n = *(const LAS f32x4*)(sW + sn * 64), b_n = *(const LAS f32x4*)(sB + sn * 64);
;                             const f32x4 k_n = *(const LAS f32x4*)(sK + sn * 64), r_n = *(const LAS f32x4*)(sR + sn * 64);
;                             const float v = vq[u16 >> 2][u16 & 3];
;                             const f32x2 vv = {v, v};
;                             f32x2 pp = S01 * (f32x2){a_[0], a_[1]}; pp = S23 * (f32x2){a_[2], a_[3]} + pp;
;                             f32x2 yy = S01 * (f32x2){rp[0], rp[1]}; yy = S23 * (f32x2){rp[2], rp[3]} + yy;
;                             float sa = pp[0] + pp[1], y = yy[0] + yy[1];
;                             sa += dpp_f<0xB1>(sa); y += dpp_f<0xB1>(y);
;                             sa += dpp_f<0x4E>(sa); y += dpp_f<0x4E>(y);
;                             sa += dpp_f<0x141>(sa); y += dpp_f<0x141>(y);
;                             sa += dpp_f<0x140>(sa); y += dpp_f<0x140>(y);
;                             sY[((s - 1) & 31) * 16 + srow] = y;
;                             const f32x2 sv = {sa, sa};
;                             S01 = S01 * (f32x2){w_[0], w_[1]} + vv * (f32x2){k_[0], k_[1]};
;                             S23 = S23 * (f32x2){w_[2], w_[3]} + vv * (f32x2){k_[2], k_[3]};
;                             S01 = sv * (f32x2){b_[0], b_[1]} + S01;
;                             S23 = sv * (f32x2){b_[2], b_[3]} + S23;
;                             rp = r_;
;                             a_ = a_n; w_ = w_n; b_ = b_n; k_ = k_n; r_ = r_n;
;                         }
	v_pk_mul_f32 v[228:229], v[166:167], v[120:121]
	v_pk_mul_f32 v[230:231], v[166:167], v[116:117]
	v_pk_fma_f32 v[228:229], v[164:165], v[122:123], v[228:229]
	v_pk_fma_f32 v[230:231], v[164:165], v[118:119], v[230:231]
	v_add_f32_e32 v236, v228, v229
	v_pk_mul_f32 v[232:233], v[224:225], v[208:209] op_sel_hi:[0,1]
	v_add_f32_e32 v237, v230, v231
	v_add_f32_dpp v236, v236, v236 quad_perm:[1,0,3,2] row_mask:0xf bank_mask:0xf bound_ctrl:1
	v_pk_mul_f32 v[234:235], v[224:225], v[210:211] op_sel_hi:[0,1]
	ds_read_b128 v[100:103], v241 offset:27136
	v_add_f32_dpp v236, v236, v236 quad_perm:[2,3,0,1] row_mask:0xf bank_mask:0xf bound_ctrl:1
	v_pk_fma_f32 v[166:167], v[166:167], v[124:125], v[232:233]
	ds_read_b128 v[104:107], v240 offset:45568
	v_add_f32_dpp v236, v236, v236 row_half_mirror row_mask:0xf bank_mask:0xf bound_ctrl:1
	v_pk_fma_f32 v[164:165], v[164:165], v[126:127], v[234:235]
	ds_read_b128 v[112:115], v240 offset:53760
	v_add_f32_dpp v236, v236, v236 row_mirror row_mask:0xf bank_mask:0xf bound_ctrl:1
	ds_read_b128 v[108:111], v241 offset:35328
	ds_read_b128 v[116:119], v240 offset:37376
	v_pk_fma_f32 v[166:167], v[204:205], v[236:237], v[166:167] op_sel_hi:[1,0,1]
	v_pk_fma_f32 v[164:165], v[206:207], v[236:237], v[164:165] op_sel_hi:[1,0,1]
	s_waitcnt lgkmcnt(5)
	v_pk_mul_f32 v[228:229], v[166:167], v[80:81]
	v_pk_mul_f32 v[230:231], v[166:167], v[212:213]
	v_pk_fma_f32 v[228:229], v[164:165], v[82:83], v[228:229]
	v_pk_fma_f32 v[230:231], v[164:165], v[214:215], v[230:231]
	v_add_f32_e32 v236, v228, v229
	v_pk_mul_f32 v[232:233], v[224:225], v[92:93] op_sel:[1,0]
	v_add_f32_e32 v238, v230, v231
	v_add_f32_dpp v236, v236, v236 quad_perm:[1,0,3,2] row_mask:0xf bank_mask:0xf bound_ctrl:1
	v_pk_mul_f32 v[234:235], v[224:225], v[94:95] op_sel:[1,0]
	ds_read_b128 v[120:123], v241 offset:27392
	v_add_f32_dpp v236, v236, v236 quad_perm:[2,3,0,1] row_mask:0xf bank_mask:0xf bound_ctrl:1
	v_pk_fma_f32 v[166:167], v[166:167], v[84:85], v[232:233]
	ds_read_b128 v[124:127], v240 offset:45824
	v_add_f32_dpp v236, v236, v236 row_half_mirror row_mask:0xf bank_mask:0xf bound_ctrl:1
	v_pk_fma_f32 v[164:165], v[164:165], v[86:87], v[234:235]
	ds_read_b128 v[208:211], v240 offset:54016
	v_add_f32_dpp v236, v236, v236 row_mirror row_mask:0xf bank_mask:0xf bound_ctrl:1
	v_add_f32_dpp v245, v245, v245 row_mirror row_mask:0xf bank_mask:0xf bound_ctrl:1
	v_add_f32_dpp v245, v238, v238 row_mirror row_mask:0xf bank_mask:0xc bound_ctrl:1
	v_pk_fma_f32 v[166:167], v[88:89], v[236:237], v[166:167] op_sel_hi:[1,0,1]
	v_pk_fma_f32 v[164:165], v[90:91], v[236:237], v[164:165] op_sel_hi:[1,0,1]
	ds_read_b128 v[204:207], v241 offset:35584
	ds_read_b128 v[212:215], v240 offset:37632
	ds_read_b128 v[220:223], v242 offset:41024
	s_waitcnt lgkmcnt(6)
	v_pk_mul_f32 v[228:229], v[166:167], v[100:101]
	v_pk_mul_f32 v[230:231], v[166:167], v[96:97]
	v_pk_fma_f32 v[228:229], v[164:165], v[102:103], v[228:229]
	v_pk_fma_f32 v[230:231], v[164:165], v[98:99], v[230:231]
	v_add_f32_e32 v236, v228, v229
	v_pk_mul_f32 v[232:233], v[226:227], v[112:113] op_sel_hi:[0,1]
	v_add_f32_e32 v239, v230, v231
	v_add_f32_dpp v236, v236, v236 quad_perm:[1,0,3,2] row_mask:0xf bank_mask:0xf bound_ctrl:1
	v_pk_mul_f32 v[234:235], v[226:227], v[114:115] op_sel_hi:[0,1]
	ds_read_b128 v[80:83], v241 offset:27648
	v_add_f32_dpp v236, v236, v236 quad_perm:[2,3,0,1] row_mask:0xf bank_mask:0xf bound_ctrl:1
	v_pk_fma_f32 v[166:167], v[166:167], v[104:105], v[232:233]
	ds_read_b128 v[84:87], v240 offset:46080
	v_add_f32_dpp v236, v236, v236 row_half_mirror row_mask:0xf bank_mask:0xf bound_ctrl:1
	v_pk_fma_f32 v[164:165], v[164:165], v[106:107], v[234:235]
	ds_read_b128 v[92:95], v240 offset:54272
	v_add_f32_dpp v236, v236, v236 row_mirror row_mask:0xf bank_mask:0xf bound_ctrl:1
	v_add_f32_dpp v246, v246, v246 row_mirror row_mask:0xf bank_mask:0xf bound_ctrl:1
	v_add_f32_dpp v246, v239, v239 row_mirror row_mask:0xf bank_mask:0xc bound_ctrl:1
	v_pk_fma_f32 v[166:167], v[108:109], v[236:237], v[166:167] op_sel_hi:[1,0,1]
	v_pk_fma_f32 v[164:165], v[110:111], v[236:237], v[164:165] op_sel_hi:[1,0,1]
	ds_read_b128 v[88:91], v241 offset:35840
	ds_read_b128 v[96:99], v240 offset:37888
	s_waitcnt lgkmcnt(6)
	v_pk_mul_f32 v[228:229], v[166:167], v[120:121]
	v_pk_mul_f32 v[230:231], v[166:167], v[116:117]
	v_pk_fma_f32 v[228:229], v[164:165], v[122:123], v[228:229]
	v_pk_fma_f32 v[230:231], v[164:165], v[118:119], v[230:231]
	v_add_f32_e32 v236, v228, v229
	v_pk_mul_f32 v[232:233], v[226:227], v[208:209] op_sel:[1,0]
	v_add_f32_e32 v202, v230, v231
	v_add_f32_dpp v236, v236, v236 quad_perm:[1,0,3,2] row_mask:0xf bank_mask:0xf bound_ctrl:1
	v_pk_mul_f32 v[234:235], v[226:227], v[210:211] op_sel:[1,0]
	ds_read_b128 v[100:103], v241 offset:27904
	v_add_f32_dpp v236, v236, v236 quad_perm:[2,3,0,1] row_mask:0xf bank_mask:0xf bound_ctrl:1
	v_pk_fma_f32 v[166:167], v[166:167], v[124:125], v[232:233]
	ds_read_b128 v[104:107], v240 offset:46336
	v_add_f32_dpp v236, v236, v236 row_half_mirror row_mask:0xf bank_mask:0xf bound_ctrl:1
	v_pk_fma_f32 v[164:165], v[164:165], v[126:127], v[234:235]
	ds_read_b128 v[112:115], v240 offset:54528
	v_add_f32_dpp v236, v236, v236 row_mirror row_mask:0xf bank_mask:0xf bound_ctrl:1
	v_add_f32_dpp v247, v247, v247 row_mirror row_mask:0xf bank_mask:0xf bound_ctrl:1
	v_add_f32_dpp v247, v202, v202 row_mirror row_mask:0xf bank_mask:0xc bound_ctrl:1
	v_pk_fma_f32 v[166:167], v[204:205], v[236:237], v[166:167] op_sel_hi:[1,0,1]
	v_pk_fma_f32 v[164:165], v[206:207], v[236:237], v[164:165] op_sel_hi:[1,0,1]
	ds_read_b128 v[108:111], v241 offset:36096
	ds_read_b128 v[116:119], v240 offset:38144
	s_waitcnt lgkmcnt(5)
; #define LAS __attribute__((address_space(3)))
; template <int CTRL> __device__ __forceinline__ float dpp_f(float x) { return __int_as_float(__builtin_amdgcn_update_dpp(0, __float_as_int(x), CTRL, 0xf, 0xf, false)); }
; __device__ __forceinline__ void phase_scan(const Params& p, LAS unsigned char* lds) {
;     ...
;                         for (int u16 = 0; u16 < 16; ++u16) {
;                             const int s = 16 * hb + u16;
;                             const int sn = (s + 1) & 31;
;                             const f32x4 a_n = *(const LAS f32x4*)(sA + sn * 64), w_n = *(const LAS f32x4*)(sW + sn * 64), b_n = *(const LAS f32x4*)(sB + sn * 64);
;                             const f32x4 k_n = *(const LAS f32x4*)(sK + sn * 64), r_n = *(const LAS f32x4*)(sR + sn * 64);
;                             const float v = vq[u16 >> 2][u16 & 3];
;                             const f32x2 vv = {v, v};
;                             f32x2 pp = S01 * (f32x2){a_[0], a_[1]}; pp = S23 * (f32x2){a_[2], a_[3]} + pp;
;                             f32x2 yy = S01 * (f32x2){rp[0], rp[1]}; yy = S23 * (f32x2){rp[2], rp[3]} + yy;
;                             float sa = pp[0] + pp[1], y = yy[0] + yy[1];
;                             sa += dpp_f<0xB1>(sa); y += dpp_f<0xB1>(y);
;                             sa += dpp_f<0x4E>(sa); y += dpp_f<0x4E>(y);
;                             sa += dpp_f<0x141>(sa); y += dpp_f<0x141>(y);
;                             sa += dpp_f<0x140>(sa); y += dpp_f<0x140>(y);
;                             sY[((s - 1) & 31) * 16 + srow] = y;
;                             const f32x2 sv = {sa, sa};
;                             S01 = S01 * (f32x2){w_[0], w_[1]} + vv * (f32x2){k_[0], k_[1]};
;                             S23 = S23 * (f32x2){w_[2], w_[3]} + vv * (f32x2){k_[2], k_[3]};
;                             S01 = sv * (f32x2){b_[0], b_[1]} + S01;
;                             S23 = sv * (f32x2){b_[2], b_[3]} + S23;
;                             rp = r_;
;                             a_ = a_n; w_ = w_n; b_ = b_n; k_ = k_n; r_ = r_n;
;                         }
	v_pk_mul_f32 v[228:229], v[166:167], v[80:81]
	v_pk_mul_f32 v[230:231], v[166:167], v[212:213]
	v_pk_fma_f32 v[228:229], v[164:165], v[82:83], v[228:229]
	v_pk_fma_f32 v[230:231], v[164:165], v[214:215], v[230:231]
	v_add_f32_e32 v236, v228, v229
	v_pk_mul_f32 v[232:233], v[216:217], v[92:93] op_sel_hi:[0,1]
	v_add_f32_e32 v203, v230, v231
	v_add_f32_dpp v236, v236, v236 quad_perm:[1,0,3,2] row_mask:0xf bank_mask:0xf bound_ctrl:1
	v_pk_mul_f32 v[234:235], v[216:217], v[94:95] op_sel_hi:[0,1]
	ds_read_b128 v[120:123], v241 offset:28160
	v_add_f32_dpp v236, v236, v236 quad_perm:[2,3,0,1] row_mask:0xf bank_mask:0xf bound_ctrl:1
	v_pk_fma_f32 v[166:167], v[166:167], v[84:85], v[232:233]
	ds_read_b128 v[124:127], v240 offset:46592
	v_add_f32_dpp v236, v236, v236 row_half_mirror row_mask:0xf bank_mask:0xf bound_ctrl:1
	v_pk_fma_f32 v[164:165], v[164:165], v[86:87], v[234:235]
	ds_read_b128 v[208:211], v240 offset:54784
	v_add_f32_dpp v236, v236, v236 row_mirror row_mask:0xf bank_mask:0xf bound_ctrl:1
	v_add_f32_dpp v248, v248, v248 row_mirror row_mask:0xf bank_mask:0xf bound_ctrl:1
	v_add_f32_dpp v248, v203, v203 row_mirror row_mask:0xf bank_mask:0xc bound_ctrl:1
	v_pk_fma_f32 v[166:167], v[88:89], v[236:237], v[166:167] op_sel_hi:[1,0,1]
	v_pk_fma_f32 v[164:165], v[90:91], v[236:237], v[164:165] op_sel_hi:[1,0,1]
	ds_read_b128 v[204:207], v241 offset:36352
	ds_read_b128 v[212:215], v240 offset:38400
	s_waitcnt lgkmcnt(5)
	v_pk_mul_f32 v[228:229], v[166:167], v[100:101]
	v_pk_mul_f32 v[230:231], v[166:167], v[96:97]
	v_pk_fma_f32 v[228:229], v[164:165], v[102:103], v[228:229]
	v_pk_fma_f32 v[230:231], v[164:165], v[98:99], v[230:231]
	v_add_f32_e32 v236, v228, v229
	v_pk_mul_f32 v[232:233], v[216:217], v[112:113] op_sel:[1,0]
	v_add_f32_e32 v128, v230, v231
	v_add_f32_dpp v236, v236, v236 quad_perm:[1,0,3,2] row_mask:0xf bank_mask:0xf bound_ctrl:1
	v_pk_mul_f32 v[234:235], v[216:217], v[114:115] op_sel:[1,0]
	ds_read_b128 v[80:83], v241 offset:28416
	v_add_f32_dpp v236, v236, v236 quad_perm:[2,3,0,1] row_mask:0xf bank_mask:0xf bound_ctrl:1
	v_pk_fma_f32 v[166:167], v[166:167], v[104:105], v[232:233]
	ds_read_b128 v[84:87], v240 offset:46848
	v_add_f32_dpp v236, v236, v236 row_half_mirror row_mask:0xf bank_mask:0xf bound_ctrl:1
	v_pk_fma_f32 v[164:165], v[164:165], v[106:107], v[234:235]
	ds_read_b128 v[92:95], v240 offset:55040
	v_add_f32_dpp v236, v236, v236 row_mirror row_mask:0xf bank_mask:0xf bound_ctrl:1
	v_add_f32_dpp v249, v249, v249 row_mirror row_mask:0xf bank_mask:0xf bound_ctrl:1
	v_add_f32_dpp v249, v128, v128 row_mirror row_mask:0xf bank_mask:0xc bound_ctrl:1
	v_pk_fma_f32 v[166:167], v[108:109], v[236:237], v[166:167] op_sel_hi:[1,0,1]
	v_pk_fma_f32 v[164:165], v[110:111], v[236:237], v[164:165] op_sel_hi:[1,0,1]
	ds_read_b128 v[88:91], v241 offset:36608
	ds_read_b128 v[96:99], v240 offset:38656
	ds_read_b128 v[224:227], v242 offset:41040
	s_waitcnt lgkmcnt(6)
	v_pk_mul_f32 v[228:229], v[166:167], v[120:121]
	v_pk_mul_f32 v[230:231], v[166:167], v[116:117]
	v_pk_fma_f32 v[228:229], v[164:165], v[122:123], v[228:229]
	v_pk_fma_f32 v[230:231], v[164:165], v[118:119], v[230:231]
	v_add_f32_e32 v236, v228, v229
	v_pk_mul_f32 v[232:233], v[218:219], v[208:209] op_sel_hi:[0,1]
	v_add_f32_e32 v129, v230, v231
	v_add_f32_dpp v236, v236, v236 quad_perm:[1,0,3,2] row_mask:0xf bank_mask:0xf bound_ctrl:1
	v_pk_mul_f32 v[234:235], v[218:219], v[210:211] op_sel_hi:[0,1]
	ds_read_b128 v[100:103], v241 offset:28672
	v_add_f32_dpp v236, v236, v236 quad_perm:[2,3,0,1] row_mask:0xf bank_mask:0xf bound_ctrl:1
	v_pk_fma_f32 v[166:167], v[166:167], v[124:125], v[232:233]
	ds_read_b128 v[104:107], v240 offset:47104
	v_add_f32_dpp v236, v236, v236 row_half_mirror row_mask:0xf bank_mask:0xf bound_ctrl:1
	v_pk_fma_f32 v[164:165], v[164:165], v[126:127], v[234:235]
	ds_read_b128 v[112:115], v240 offset:55296
	v_add_f32_dpp v236, v236, v236 row_mirror row_mask:0xf bank_mask:0xf bound_ctrl:1
	v_add_f32_dpp v250, v250, v250 row_mirror row_mask:0xf bank_mask:0xf bound_ctrl:1
	v_add_f32_dpp v250, v129, v129 row_mirror row_mask:0xf bank_mask:0xc bound_ctrl:1
	v_pk_fma_f32 v[166:167], v[204:205], v[236:237], v[166:167] op_sel_hi:[1,0,1]
	v_pk_fma_f32 v[164:165], v[206:207], v[236:237], v[164:165] op_sel_hi:[1,0,1]
	ds_read_b128 v[108:111], v241 offset:36864
	ds_read_b128 v[116:119], v240 offset:38912
	s_waitcnt lgkmcnt(6)
	v_pk_mul_f32 v[228:229], v[166:167], v[80:81]
	v_pk_mul_f32 v[230:231], v[166:167], v[212:213]
	v_pk_fma_f32 v[228:229], v[164:165], v[82:83], v[228:229]
	v_pk_fma_f32 v[230:231], v[164:165], v[214:215], v[230:231]
	v_add_f32_e32 v236, v228, v229
	v_pk_mul_f32 v[232:233], v[218:219], v[92:93] op_sel:[1,0]
	v_add_f32_e32 v78, v230, v231
	v_add_f32_dpp v236, v236, v236 quad_perm:[1,0,3,2] row_mask:0xf bank_mask:0xf bound_ctrl:1
	v_pk_mul_f32 v[234:235], v[218:219], v[94:95] op_sel:[1,0]
	ds_read_b128 v[120:123], v241 offset:28928
	v_add_f32_dpp v236, v236, v236 quad_perm:[2,3,0,1] row_mask:0xf bank_mask:0xf bound_ctrl:1
	v_pk_fma_f32 v[166:167], v[166:167], v[84:85], v[232:233]
	ds_read_b128 v[124:127], v240 offset:47360
	v_add_f32_dpp v236, v236, v236 row_half_mirror row_mask:0xf bank_mask:0xf bound_ctrl:1
	v_pk_fma_f32 v[164:165], v[164:165], v[86:87], v[234:235]
	ds_read_b128 v[208:211], v240 offset:55552
	v_add_f32_dpp v236, v236, v236 row_mirror row_mask:0xf bank_mask:0xf bound_ctrl:1
	v_add_f32_dpp v251, v251, v251 row_mirror row_mask:0xf bank_mask:0xf bound_ctrl:1
	v_add_f32_dpp v251, v78, v78 row_mirror row_mask:0xf bank_mask:0xc bound_ctrl:1
	v_pk_fma_f32 v[166:167], v[88:89], v[236:237], v[166:167] op_sel_hi:[1,0,1]
	v_pk_fma_f32 v[164:165], v[90:91], v[236:237], v[164:165] op_sel_hi:[1,0,1]
	ds_read_b128 v[204:207], v241 offset:37120
	ds_read_b128 v[212:215], v240 offset:39168
	s_waitcnt lgkmcnt(5)
; #define LAS __attribute__((address_space(3)))
; template <int CTRL> __device__ __forceinline__ float dpp_f(float x) { return __int_as_float(__builtin_amdgcn_update_dpp(0, __float_as_int(x), CTRL, 0xf, 0xf, false)); }
; __device__ __forceinline__ void phase_scan(const Params& p, LAS unsigned char* lds) {
;     ...
;                         for (int u16 = 0; u16 < 16; ++u16) {
;                             const int s = 16 * hb + u16;
;                             const int sn = (s + 1) & 31;
;                             const f32x4 a_n = *(const LAS f32x4*)(sA + sn * 64), w_n = *(const LAS f32x4*)(sW + sn * 64), b_n = *(const LAS f32x4*)(sB + sn * 64);
;                             const f32x4 k_n = *(const LAS f32x4*)(sK + sn * 64), r_n = *(const LAS f32x4*)(sR + sn * 64);
;                             const float v = vq[u16 >> 2][u16 & 3];
;                             const f32x2 vv = {v, v};
;                             f32x2 pp = S01 * (f32x2){a_[0], a_[1]}; pp = S23 * (f32x2){a_[2], a_[3]} + pp;
;                             f32x2 yy = S01 * (f32x2){rp[0], rp[1]}; yy = S23 * (f32x2){rp[2], rp[3]} + yy;
;                             float sa = pp[0] + pp[1], y = yy[0] + yy[1];
;                             sa += dpp_f<0xB1>(sa); y += dpp_f<0xB1>(y);
;                             sa += dpp_f<0x4E>(sa); y += dpp_f<0x4E>(y);
;                             sa += dpp_f<0x141>(sa); y += dpp_f<0x141>(y);
;                             sa += dpp_f<0x140>(sa); y += dpp_f<0x140>(y);
;                             sY[((s - 1) & 31) * 16 + srow] = y;
;                             const f32x2 sv = {sa, sa};
;                             S01 = S01 * (f32x2){w_[0], w_[1]} + vv * (f32x2){k_[0], k_[1]};
;                             S23 = S23 * (f32x2){w_[2], w_[3]} + vv * (f32x2){k_[2], k_[3]};
;                             S01 = sv * (f32x2){b_[0], b_[1]} + S01;
;                             S23 = sv * (f32x2){b_[2], b_[3]} + S23;
;                             rp = r_;
;                             a_ = a_n; w_ = w_n; b_ = b_n; k_ = k_n; r_ = r_n;
;                         }
	v_pk_mul_f32 v[228:229], v[166:167], v[100:101]
	v_pk_mul_f32 v[230:231], v[166:167], v[96:97]
	v_pk_fma_f32 v[228:229], v[164:165], v[102:103], v[228:229]
	v_pk_fma_f32 v[230:231], v[164:165], v[98:99], v[230:231]
	v_add_f32_e32 v236, v228, v229
	v_pk_mul_f32 v[232:233], v[220:221], v[112:113] op_sel_hi:[0,1]
	v_add_f32_e32 v79, v230, v231
	v_add_f32_dpp v236, v236, v236 quad_perm:[1,0,3,2] row_mask:0xf bank_mask:0xf bound_ctrl:1
	v_pk_mul_f32 v[234:235], v[220:221], v[114:115] op_sel_hi:[0,1]
	ds_read_b128 v[80:83], v241 offset:29184
	v_add_f32_dpp v236, v236, v236 quad_perm:[2,3,0,1] row_mask:0xf bank_mask:0xf bound_ctrl:1
	v_pk_fma_f32 v[166:167], v[166:167], v[104:105], v[232:233]
	ds_read_b128 v[84:87], v240 offset:47616
	v_add_f32_dpp v236, v236, v236 row_half_mirror row_mask:0xf bank_mask:0xf bound_ctrl:1
	v_pk_fma_f32 v[164:165], v[164:165], v[106:107], v[234:235]
	ds_read_b128 v[92:95], v240 offset:55808
	v_add_f32_dpp v236, v236, v236 row_mirror row_mask:0xf bank_mask:0xf bound_ctrl:1
	v_add_f32_dpp v237, v237, v237 row_mirror row_mask:0xf bank_mask:0xf bound_ctrl:1
	v_add_f32_dpp v237, v79, v79 row_mirror row_mask:0xf bank_mask:0xc bound_ctrl:1
	v_pk_fma_f32 v[166:167], v[108:109], v[236:237], v[166:167] op_sel_hi:[1,0,1]
	v_pk_fma_f32 v[164:165], v[110:111], v[236:237], v[164:165] op_sel_hi:[1,0,1]
	ds_read_b128 v[88:91], v241 offset:37376
	ds_read_b128 v[96:99], v240 offset:39424
	s_waitcnt lgkmcnt(5)
	v_pk_mul_f32 v[228:229], v[166:167], v[120:121]
	v_pk_mul_f32 v[230:231], v[166:167], v[116:117]
	v_pk_fma_f32 v[228:229], v[164:165], v[122:123], v[228:229]
	v_pk_fma_f32 v[230:231], v[164:165], v[118:119], v[230:231]
	v_add_f32_e32 v236, v228, v229
	v_pk_mul_f32 v[232:233], v[220:221], v[208:209] op_sel:[1,0]
	v_add_f32_e32 v238, v230, v231
	v_add_f32_dpp v236, v236, v236 quad_perm:[1,0,3,2] row_mask:0xf bank_mask:0xf bound_ctrl:1
	v_pk_mul_f32 v[234:235], v[220:221], v[210:211] op_sel:[1,0]
	ds_read_b128 v[100:103], v241 offset:29440
	v_add_f32_dpp v236, v236, v236 quad_perm:[2,3,0,1] row_mask:0xf bank_mask:0xf bound_ctrl:1
	v_pk_fma_f32 v[166:167], v[166:167], v[124:125], v[232:233]
	ds_read_b128 v[104:107], v240 offset:47872
	v_add_f32_dpp v236, v236, v236 row_half_mirror row_mask:0xf bank_mask:0xf bound_ctrl:1
	v_pk_fma_f32 v[164:165], v[164:165], v[126:127], v[234:235]
	ds_read_b128 v[112:115], v240 offset:56064
	v_add_f32_dpp v236, v236, v236 row_mirror row_mask:0xf bank_mask:0xf bound_ctrl:1
	v_add_f32_dpp v245, v245, v245 row_half_mirror row_mask:0xf bank_mask:0xf bound_ctrl:1
	v_add_f32_dpp v246, v246, v246 row_half_mirror row_mask:0xf bank_mask:0xf bound_ctrl:1
	v_pk_fma_f32 v[166:167], v[204:205], v[236:237], v[166:167] op_sel_hi:[1,0,1]
	v_pk_fma_f32 v[164:165], v[206:207], v[236:237], v[164:165] op_sel_hi:[1,0,1]
	ds_read_b128 v[108:111], v241 offset:37632
	ds_read_b128 v[116:119], v240 offset:39680
	ds_read_b128 v[216:219], v242 offset:41056
	s_waitcnt lgkmcnt(6)
	v_pk_mul_f32 v[228:229], v[166:167], v[80:81]
	v_pk_mul_f32 v[230:231], v[166:167], v[212:213]
	v_pk_fma_f32 v[228:229], v[164:165], v[82:83], v[228:229]
	v_pk_fma_f32 v[230:231], v[164:165], v[214:215], v[230:231]
	v_add_f32_e32 v236, v228, v229
	v_pk_mul_f32 v[232:233], v[222:223], v[92:93] op_sel_hi:[0,1]
	v_add_f32_e32 v239, v230, v231
	v_add_f32_dpp v236, v236, v236 quad_perm:[1,0,3,2] row_mask:0xf bank_mask:0xf bound_ctrl:1
	v_pk_mul_f32 v[234:235], v[222:223], v[94:95] op_sel_hi:[0,1]
	ds_read_b128 v[120:123], v241 offset:29696
	v_add_f32_dpp v236, v236, v236 quad_perm:[2,3,0,1] row_mask:0xf bank_mask:0xf bound_ctrl:1
	v_pk_fma_f32 v[166:167], v[166:167], v[84:85], v[232:233]
	ds_read_b128 v[124:127], v240 offset:48128
	v_add_f32_dpp v236, v236, v236 row_half_mirror row_mask:0xf bank_mask:0xf bound_ctrl:1
	v_pk_fma_f32 v[164:165], v[164:165], v[86:87], v[234:235]
	ds_read_b128 v[208:211], v240 offset:56320
	v_add_f32_dpp v236, v236, v236 row_mirror row_mask:0xf bank_mask:0xf bound_ctrl:1
	v_add_f32_dpp v247, v247, v247 row_half_mirror row_mask:0xf bank_mask:0xf bound_ctrl:1
	v_add_f32_dpp v248, v248, v248 row_half_mirror row_mask:0xf bank_mask:0xf bound_ctrl:1
	v_pk_fma_f32 v[166:167], v[88:89], v[236:237], v[166:167] op_sel_hi:[1,0,1]
	v_pk_fma_f32 v[164:165], v[90:91], v[236:237], v[164:165] op_sel_hi:[1,0,1]
	ds_read_b128 v[204:207], v241 offset:37888
	ds_read_b128 v[212:215], v240 offset:39936
	s_waitcnt lgkmcnt(6)
	v_pk_mul_f32 v[228:229], v[166:167], v[100:101]
	v_pk_mul_f32 v[230:231], v[166:167], v[96:97]
	v_pk_fma_f32 v[228:229], v[164:165], v[102:103], v[228:229]
	v_pk_fma_f32 v[230:231], v[164:165], v[98:99], v[230:231]
	v_add_f32_e32 v236, v228, v229
	v_pk_mul_f32 v[232:233], v[222:223], v[112:113] op_sel:[1,0]
	v_add_f32_e32 v202, v230, v231
	v_add_f32_dpp v236, v236, v236 quad_perm:[1,0,3,2] row_mask:0xf bank_mask:0xf bound_ctrl:1
	v_pk_mul_f32 v[234:235], v[222:223], v[114:115] op_sel:[1,0]
	ds_read_b128 v[80:83], v241 offset:29952
	v_add_f32_dpp v236, v236, v236 quad_perm:[2,3,0,1] row_mask:0xf bank_mask:0xf bound_ctrl:1
	v_pk_fma_f32 v[166:167], v[166:167], v[104:105], v[232:233]
	ds_read_b128 v[84:87], v240 offset:48384
	v_add_f32_dpp v236, v236, v236 row_half_mirror row_mask:0xf bank_mask:0xf bound_ctrl:1
	v_pk_fma_f32 v[164:165], v[164:165], v[106:107], v[234:235]
	ds_read_b128 v[92:95], v240 offset:56576
	v_add_f32_dpp v236, v236, v236 row_mirror row_mask:0xf bank_mask:0xf bound_ctrl:1
	v_add_f32_dpp v245, v249, v249 row_half_mirror row_mask:0xf bank_mask:0xa bound_ctrl:1
	v_add_f32_dpp v246, v250, v250 row_half_mirror row_mask:0xf bank_mask:0xa bound_ctrl:1
	v_pk_fma_f32 v[166:167], v[108:109], v[236:237], v[166:167] op_sel_hi:[1,0,1]
	v_pk_fma_f32 v[164:165], v[110:111], v[236:237], v[164:165] op_sel_hi:[1,0,1]
	ds_read_b128 v[88:91], v241 offset:38144
	ds_read_b128 v[96:99], v240 offset:40192
	s_waitcnt lgkmcnt(5)
; #define LAS __attribute__((address_space(3)))
; template <int CTRL> __device__ __forceinline__ float dpp_f(float x) { return __int_as_float(__builtin_amdgcn_update_dpp(0, __float_as_int(x), CTRL, 0xf, 0xf, false)); }
; __device__ __forceinline__ void phase_scan(const Params& p, LAS unsigned char* lds) {
;     ...
;                         for (int u16 = 0; u16 < 16; ++u16) {
;                             const int s = 16 * hb + u16;
;                             const int sn = (s + 1) & 31;
;                             const f32x4 a_n = *(const LAS f32x4*)(sA + sn * 64), w_n = *(const LAS f32x4*)(sW + sn * 64), b_n = *(const LAS f32x4*)(sB + sn * 64);
;                             const f32x4 k_n = *(const LAS f32x4*)(sK + sn * 64), r_n = *(const LAS f32x4*)(sR + sn * 64);
;                             const float v = vq[u16 >> 2][u16 & 3];
;                             const f32x2 vv = {v, v};
;                             f32x2 pp = S01 * (f32x2){a_[0], a_[1]}; pp = S23 * (f32x2){a_[2], a_[3]} + pp;
;                             f32x2 yy = S01 * (f32x2){rp[0], rp[1]}; yy = S23 * (f32x2){rp[2], rp[3]} + yy;
;                             float sa = pp[0] + pp[1], y = yy[0] + yy[1];
;                             sa += dpp_f<0xB1>(sa); y += dpp_f<0xB1>(y);
;                             sa += dpp_f<0x4E>(sa); y += dpp_f<0x4E>(y);
;                             sa += dpp_f<0x141>(sa); y += dpp_f<0x141>(y);
;                             sa += dpp_f<0x140>(sa); y += dpp_f<0x140>(y);
;                             sY[((s - 1) & 31) * 16 + srow] = y;
;                             const f32x2 sv = {sa, sa};
;                             S01 = S01 * (f32x2){w_[0], w_[1]} + vv * (f32x2){k_[0], k_[1]};
;                             S23 = S23 * (f32x2){w_[2], w_[3]} + vv * (f32x2){k_[2], k_[3]};
;                             S01 = sv * (f32x2){b_[0], b_[1]} + S01;
;                             S23 = sv * (f32x2){b_[2], b_[3]} + S23;
;                             rp = r_;
;                             a_ = a_n; w_ = w_n; b_ = b_n; k_ = k_n; r_ = r_n;
;                         }
	v_pk_mul_f32 v[228:229], v[166:167], v[120:121]
	v_pk_mul_f32 v[230:231], v[166:167], v[116:117]
	v_pk_fma_f32 v[228:229], v[164:165], v[122:123], v[228:229]
	v_pk_fma_f32 v[230:231], v[164:165], v[118:119], v[230:231]
	v_add_f32_e32 v236, v228, v229
	v_pk_mul_f32 v[232:233], v[224:225], v[208:209] op_sel_hi:[0,1]
	v_add_f32_e32 v203, v230, v231
	v_add_f32_dpp v236, v236, v236 quad_perm:[1,0,3,2] row_mask:0xf bank_mask:0xf bound_ctrl:1
	v_pk_mul_f32 v[234:235], v[224:225], v[210:211] op_sel_hi:[0,1]
	ds_read_b128 v[100:103], v241 offset:30208
	v_add_f32_dpp v236, v236, v236 quad_perm:[2,3,0,1] row_mask:0xf bank_mask:0xf bound_ctrl:1
	v_pk_fma_f32 v[166:167], v[166:167], v[124:125], v[232:233]
	ds_read_b128 v[104:107], v240 offset:48640
	v_add_f32_dpp v236, v236, v236 row_half_mirror row_mask:0xf bank_mask:0xf bound_ctrl:1
	v_pk_fma_f32 v[164:165], v[164:165], v[126:127], v[234:235]
	ds_read_b128 v[112:115], v240 offset:56832
	v_add_f32_dpp v236, v236, v236 row_mirror row_mask:0xf bank_mask:0xf bound_ctrl:1
	v_add_f32_dpp v247, v251, v251 row_half_mirror row_mask:0xf bank_mask:0xa bound_ctrl:1
	v_add_f32_dpp v248, v237, v237 row_half_mirror row_mask:0xf bank_mask:0xa bound_ctrl:1
	v_pk_fma_f32 v[166:167], v[204:205], v[236:237], v[166:167] op_sel_hi:[1,0,1]
	v_pk_fma_f32 v[164:165], v[206:207], v[236:237], v[164:165] op_sel_hi:[1,0,1]
	ds_read_b128 v[108:111], v241 offset:38400
	ds_read_b128 v[116:119], v240 offset:40448
	s_waitcnt lgkmcnt(5)
	v_pk_mul_f32 v[228:229], v[166:167], v[80:81]
	v_pk_mul_f32 v[230:231], v[166:167], v[212:213]
	v_pk_fma_f32 v[228:229], v[164:165], v[82:83], v[228:229]
	v_pk_fma_f32 v[230:231], v[164:165], v[214:215], v[230:231]
	v_add_f32_e32 v236, v228, v229
	v_pk_mul_f32 v[232:233], v[224:225], v[92:93] op_sel:[1,0]
	v_add_f32_e32 v128, v230, v231
	v_add_f32_dpp v236, v236, v236 quad_perm:[1,0,3,2] row_mask:0xf bank_mask:0xf bound_ctrl:1
	v_pk_mul_f32 v[234:235], v[224:225], v[94:95] op_sel:[1,0]
	ds_read_b128 v[120:123], v241 offset:30464
	v_add_f32_dpp v236, v236, v236 quad_perm:[2,3,0,1] row_mask:0xf bank_mask:0xf bound_ctrl:1
	v_pk_fma_f32 v[166:167], v[166:167], v[84:85], v[232:233]
	ds_read_b128 v[124:127], v240 offset:48896
	v_add_f32_dpp v236, v236, v236 row_half_mirror row_mask:0xf bank_mask:0xf bound_ctrl:1
	v_pk_fma_f32 v[164:165], v[164:165], v[86:87], v[234:235]
	ds_read_b128 v[208:211], v240 offset:57088
	v_add_f32_dpp v236, v236, v236 row_mirror row_mask:0xf bank_mask:0xf bound_ctrl:1
	v_add_f32_dpp v245, v245, v245 quad_perm:[1,0,3,2] row_mask:0xf bank_mask:0xf bound_ctrl:1
	v_add_f32_dpp v246, v246, v246 quad_perm:[1,0,3,2] row_mask:0xf bank_mask:0xf bound_ctrl:1
	v_pk_fma_f32 v[166:167], v[88:89], v[236:237], v[166:167] op_sel_hi:[1,0,1]
	v_pk_fma_f32 v[164:165], v[90:91], v[236:237], v[164:165] op_sel_hi:[1,0,1]
	ds_read_b128 v[204:207], v241 offset:38656
	ds_read_b128 v[212:215], v240 offset:40704
	ds_read_b128 v[220:223], v242 offset:41072
	s_waitcnt lgkmcnt(6)
	v_pk_mul_f32 v[228:229], v[166:167], v[100:101]
	v_pk_mul_f32 v[230:231], v[166:167], v[96:97]
	v_pk_fma_f32 v[228:229], v[164:165], v[102:103], v[228:229]
	v_pk_fma_f32 v[230:231], v[164:165], v[98:99], v[230:231]
	v_add_f32_e32 v236, v228, v229
	v_pk_mul_f32 v[232:233], v[226:227], v[112:113] op_sel_hi:[0,1]
	v_add_f32_e32 v129, v230, v231
	v_add_f32_dpp v236, v236, v236 quad_perm:[1,0,3,2] row_mask:0xf bank_mask:0xf bound_ctrl:1
	v_pk_mul_f32 v[234:235], v[226:227], v[114:115] op_sel_hi:[0,1]
	ds_read_b128 v[80:83], v241 offset:30720
	v_add_f32_dpp v236, v236, v236 quad_perm:[2,3,0,1] row_mask:0xf bank_mask:0xf bound_ctrl:1
	v_pk_fma_f32 v[166:167], v[166:167], v[104:105], v[232:233]
	ds_read_b128 v[84:87], v240 offset:49152
	v_add_f32_dpp v236, v236, v236 row_half_mirror row_mask:0xf bank_mask:0xf bound_ctrl:1
	v_pk_fma_f32 v[164:165], v[164:165], v[106:107], v[234:235]
	ds_read_b128 v[92:95], v240 offset:57344
	v_add_f32_dpp v236, v236, v236 row_mirror row_mask:0xf bank_mask:0xf bound_ctrl:1
	v_add_f32_dpp v247, v247, v247 quad_perm:[1,0,3,2] row_mask:0xf bank_mask:0xf bound_ctrl:1
	v_add_f32_dpp v248, v248, v248 quad_perm:[1,0,3,2] row_mask:0xf bank_mask:0xf bound_ctrl:1
	v_pk_fma_f32 v[166:167], v[108:109], v[236:237], v[166:167] op_sel_hi:[1,0,1]
	v_pk_fma_f32 v[164:165], v[110:111], v[236:237], v[164:165] op_sel_hi:[1,0,1]
	ds_read_b128 v[88:91], v241 offset:38912
	ds_read_b128 v[96:99], v240 offset:40960
	s_waitcnt lgkmcnt(6)
	v_pk_mul_f32 v[228:229], v[166:167], v[120:121]
	v_pk_mul_f32 v[230:231], v[166:167], v[116:117]
	v_pk_fma_f32 v[228:229], v[164:165], v[122:123], v[228:229]
	v_pk_fma_f32 v[230:231], v[164:165], v[118:119], v[230:231]
	v_add_f32_e32 v236, v228, v229
	v_pk_mul_f32 v[232:233], v[226:227], v[208:209] op_sel:[1,0]
	v_add_f32_e32 v78, v230, v231
	v_add_f32_dpp v236, v236, v236 quad_perm:[1,0,3,2] row_mask:0xf bank_mask:0xf bound_ctrl:1
	v_pk_mul_f32 v[234:235], v[226:227], v[210:211] op_sel:[1,0]
	ds_read_b128 v[100:103], v241 offset:30976
	v_add_f32_dpp v236, v236, v236 quad_perm:[2,3,0,1] row_mask:0xf bank_mask:0xf bound_ctrl:1
	v_pk_fma_f32 v[166:167], v[166:167], v[124:125], v[232:233]
	ds_read_b128 v[104:107], v240 offset:49408
	v_add_f32_dpp v236, v236, v236 row_half_mirror row_mask:0xf bank_mask:0xf bound_ctrl:1
	v_pk_fma_f32 v[164:165], v[164:165], v[126:127], v[234:235]
	ds_read_b128 v[112:115], v240 offset:57600
	v_add_f32_dpp v236, v236, v236 row_mirror row_mask:0xf bank_mask:0xf bound_ctrl:1
	v_add_f32_dpp v245, v245, v245 quad_perm:[2,3,0,1] row_mask:0xf bank_mask:0xf bound_ctrl:1
	v_add_f32_dpp v246, v246, v246 quad_perm:[2,3,0,1] row_mask:0xf bank_mask:0xf bound_ctrl:1
	v_pk_fma_f32 v[166:167], v[204:205], v[236:237], v[166:167] op_sel_hi:[1,0,1]
	v_pk_fma_f32 v[164:165], v[206:207], v[236:237], v[164:165] op_sel_hi:[1,0,1]
	ds_read_b128 v[108:111], v241 offset:39168
	ds_read_b128 v[116:119], v240 offset:41216
	s_waitcnt lgkmcnt(5)
; #define LAS __attribute__((address_space(3)))
; template <int CTRL> __device__ __forceinline__ float dpp_f(float x) { return __int_as_float(__builtin_amdgcn_update_dpp(0, __float_as_int(x), CTRL, 0xf, 0xf, false)); }
; __device__ __forceinline__ void phase_scan(const Params& p, LAS unsigned char* lds) {
;     ...
;                         for (int u16 = 0; u16 < 16; ++u16) {
;                             const int s = 16 * hb + u16;
;                             const int sn = (s + 1) & 31;
;                             const f32x4 a_n = *(const LAS f32x4*)(sA + sn * 64), w_n = *(const LAS f32x4*)(sW + sn * 64), b_n = *(const LAS f32x4*)(sB + sn * 64);
;                             const f32x4 k_n = *(const LAS f32x4*)(sK + sn * 64), r_n = *(const LAS f32x4*)(sR + sn * 64);
;                             const float v = vq[u16 >> 2][u16 & 3];
;                             const f32x2 vv = {v, v};
;                             f32x2 pp = S01 * (f32x2){a_[0], a_[1]}; pp = S23 * (f32x2){a_[2], a_[3]} + pp;
;                             f32x2 yy = S01 * (f32x2){rp[0], rp[1]}; yy = S23 * (f32x2){rp[2], rp[3]} + yy;
;                             float sa = pp[0] + pp[1], y = yy[0] + yy[1];
;                             sa += dpp_f<0xB1>(sa); y += dpp_f<0xB1>(y);
;                             sa += dpp_f<0x4E>(sa); y += dpp_f<0x4E>(y);
;                             sa += dpp_f<0x141>(sa); y += dpp_f<0x141>(y);
;                             sa += dpp_f<0x140>(sa); y += dpp_f<0x140>(y);
;                             sY[((s - 1) & 31) * 16 + srow] = y;
;                             const f32x2 sv = {sa, sa};
;                             S01 = S01 * (f32x2){w_[0], w_[1]} + vv * (f32x2){k_[0], k_[1]};
;                             S23 = S23 * (f32x2){w_[2], w_[3]} + vv * (f32x2){k_[2], k_[3]};
;                             S01 = sv * (f32x2){b_[0], b_[1]} + S01;
;                             S23 = sv * (f32x2){b_[2], b_[3]} + S23;
;                             rp = r_;
;                             a_ = a_n; w_ = w_n; b_ = b_n; k_ = k_n; r_ = r_n;
;                         }
	v_pk_mul_f32 v[228:229], v[166:167], v[80:81]
	v_pk_mul_f32 v[230:231], v[166:167], v[212:213]
	v_pk_fma_f32 v[228:229], v[164:165], v[82:83], v[228:229]
	v_pk_fma_f32 v[230:231], v[164:165], v[214:215], v[230:231]
	v_add_f32_e32 v236, v228, v229
	v_pk_mul_f32 v[232:233], v[216:217], v[92:93] op_sel_hi:[0,1]
	v_add_f32_e32 v79, v230, v231
	v_add_f32_dpp v236, v236, v236 quad_perm:[1,0,3,2] row_mask:0xf bank_mask:0xf bound_ctrl:1
	v_pk_mul_f32 v[234:235], v[216:217], v[94:95] op_sel_hi:[0,1]
	ds_read_b128 v[120:123], v241 offset:31232
	v_add_f32_dpp v236, v236, v236 quad_perm:[2,3,0,1] row_mask:0xf bank_mask:0xf bound_ctrl:1
	v_pk_fma_f32 v[166:167], v[166:167], v[84:85], v[232:233]
	ds_read_b128 v[124:127], v240 offset:49664
	v_add_f32_dpp v236, v236, v236 row_half_mirror row_mask:0xf bank_mask:0xf bound_ctrl:1
	v_pk_fma_f32 v[164:165], v[164:165], v[86:87], v[234:235]
	ds_read_b128 v[208:211], v240 offset:57856
	v_add_f32_dpp v236, v236, v236 row_mirror row_mask:0xf bank_mask:0xf bound_ctrl:1
	v_add_f32_dpp v247, v247, v247 quad_perm:[2,3,0,1] row_mask:0xf bank_mask:0xf bound_ctrl:1
	v_add_f32_dpp v248, v248, v248 quad_perm:[2,3,0,1] row_mask:0xf bank_mask:0xf bound_ctrl:1
	v_pk_fma_f32 v[166:167], v[88:89], v[236:237], v[166:167] op_sel_hi:[1,0,1]
	v_pk_fma_f32 v[164:165], v[90:91], v[236:237], v[164:165] op_sel_hi:[1,0,1]
	ds_read_b128 v[204:207], v241 offset:39424
	ds_read_b128 v[212:215], v240 offset:41472
	s_waitcnt lgkmcnt(5)
	v_pk_mul_f32 v[228:229], v[166:167], v[100:101]
	v_pk_mul_f32 v[230:231], v[166:167], v[96:97]
	v_pk_fma_f32 v[228:229], v[164:165], v[102:103], v[228:229]
	v_pk_fma_f32 v[230:231], v[164:165], v[98:99], v[230:231]
	v_add_f32_e32 v236, v228, v229
	v_pk_mul_f32 v[232:233], v[216:217], v[112:113] op_sel:[1,0]
	v_add_f32_e32 v249, v230, v231
	v_add_f32_dpp v236, v236, v236 quad_perm:[1,0,3,2] row_mask:0xf bank_mask:0xf bound_ctrl:1
	v_pk_mul_f32 v[234:235], v[216:217], v[114:115] op_sel:[1,0]
	ds_read_b128 v[80:83], v241 offset:31488
	v_add_f32_dpp v236, v236, v236 quad_perm:[2,3,0,1] row_mask:0xf bank_mask:0xf bound_ctrl:1
	v_pk_fma_f32 v[166:167], v[166:167], v[104:105], v[232:233]
	ds_read_b128 v[84:87], v240 offset:49920
	v_add_f32_dpp v236, v236, v236 row_half_mirror row_mask:0xf bank_mask:0xf bound_ctrl:1
	v_pk_fma_f32 v[164:165], v[164:165], v[106:107], v[234:235]
	ds_read_b128 v[92:95], v240 offset:58112
	v_add_f32_dpp v236, v236, v236 row_mirror row_mask:0xf bank_mask:0xf bound_ctrl:1
	ds_write_b32 v244, v245 offset:0
	ds_write_b32 v244, v246 offset:64
	v_pk_fma_f32 v[166:167], v[108:109], v[236:237], v[166:167] op_sel_hi:[1,0,1]
	v_pk_fma_f32 v[164:165], v[110:111], v[236:237], v[164:165] op_sel_hi:[1,0,1]
	ds_read_b128 v[88:91], v241 offset:39680
	ds_read_b128 v[96:99], v240 offset:41728
	s_waitcnt lgkmcnt(7)
	v_pk_mul_f32 v[228:229], v[166:167], v[120:121]
	v_pk_mul_f32 v[230:231], v[166:167], v[116:117]
	v_pk_fma_f32 v[228:229], v[164:165], v[122:123], v[228:229]
	v_pk_fma_f32 v[230:231], v[164:165], v[118:119], v[230:231]
	v_add_f32_e32 v236, v228, v229
	v_pk_mul_f32 v[232:233], v[218:219], v[208:209] op_sel_hi:[0,1]
	v_add_f32_e32 v250, v230, v231
	v_add_f32_dpp v236, v236, v236 quad_perm:[1,0,3,2] row_mask:0xf bank_mask:0xf bound_ctrl:1
	v_pk_mul_f32 v[234:235], v[218:219], v[210:211] op_sel_hi:[0,1]
	ds_read_b128 v[100:103], v241 offset:31744
	v_add_f32_dpp v236, v236, v236 quad_perm:[2,3,0,1] row_mask:0xf bank_mask:0xf bound_ctrl:1
	v_pk_fma_f32 v[166:167], v[166:167], v[124:125], v[232:233]
	ds_read_b128 v[104:107], v240 offset:50176
	v_add_f32_dpp v236, v236, v236 row_half_mirror row_mask:0xf bank_mask:0xf bound_ctrl:1
	v_pk_fma_f32 v[164:165], v[164:165], v[126:127], v[234:235]
	ds_read_b128 v[112:115], v240 offset:58368
	v_add_f32_dpp v236, v236, v236 row_mirror row_mask:0xf bank_mask:0xf bound_ctrl:1
	ds_write_b32 v244, v247 offset:128
	ds_write_b32 v244, v248 offset:192
	v_pk_fma_f32 v[166:167], v[204:205], v[236:237], v[166:167] op_sel_hi:[1,0,1]
	v_pk_fma_f32 v[164:165], v[206:207], v[236:237], v[164:165] op_sel_hi:[1,0,1]
	ds_read_b128 v[108:111], v241 offset:39936
	ds_read_b128 v[116:119], v240 offset:41984
	s_waitcnt lgkmcnt(7)
	v_pk_mul_f32 v[228:229], v[166:167], v[80:81]
	v_pk_mul_f32 v[230:231], v[166:167], v[212:213]
	v_pk_fma_f32 v[228:229], v[164:165], v[82:83], v[228:229]
	v_pk_fma_f32 v[230:231], v[164:165], v[214:215], v[230:231]
	v_add_f32_e32 v236, v228, v229
	v_pk_mul_f32 v[232:233], v[218:219], v[92:93] op_sel:[1,0]
	v_add_f32_e32 v251, v230, v231
	v_add_f32_dpp v236, v236, v236 quad_perm:[1,0,3,2] row_mask:0xf bank_mask:0xf bound_ctrl:1
	v_pk_mul_f32 v[234:235], v[218:219], v[94:95] op_sel:[1,0]
	ds_read_b128 v[120:123], v241 offset:32000
	v_add_f32_dpp v236, v236, v236 quad_perm:[2,3,0,1] row_mask:0xf bank_mask:0xf bound_ctrl:1
	v_pk_fma_f32 v[166:167], v[166:167], v[84:85], v[232:233]
	ds_read_b128 v[124:127], v240 offset:50432
	v_add_f32_dpp v236, v236, v236 row_half_mirror row_mask:0xf bank_mask:0xf bound_ctrl:1
	v_pk_fma_f32 v[164:165], v[164:165], v[86:87], v[234:235]
	ds_read_b128 v[208:211], v240 offset:58624
	v_add_f32_dpp v236, v236, v236 row_mirror row_mask:0xf bank_mask:0xf bound_ctrl:1
	v_add_f32_dpp v238, v238, v238 row_mirror row_mask:0xf bank_mask:0xf bound_ctrl:1
	v_add_f32_dpp v238, v249, v249 row_mirror row_mask:0xf bank_mask:0xc bound_ctrl:1
	v_pk_fma_f32 v[166:167], v[88:89], v[236:237], v[166:167] op_sel_hi:[1,0,1]
	v_pk_fma_f32 v[164:165], v[90:91], v[236:237], v[164:165] op_sel_hi:[1,0,1]
	ds_read_b128 v[204:207], v241 offset:40192
	ds_read_b128 v[212:215], v240 offset:42240
	s_waitcnt lgkmcnt(5)
; #define LAS __attribute__((address_space(3)))
; template <int CTRL> __device__ __forceinline__ float dpp_f(float x) { return __int_as_float(__builtin_amdgcn_update_dpp(0, __float_as_int(x), CTRL, 0xf, 0xf, false)); }
; __device__ __forceinline__ void phase_scan(const Params& p, LAS unsigned char* lds) {
;     ...
;                         for (int u16 = 0; u16 < 16; ++u16) {
;                             const int s = 16 * hb + u16;
;                             const int sn = (s + 1) & 31;
;                             const f32x4 a_n = *(const LAS f32x4*)(sA + sn * 64), w_n = *(const LAS f32x4*)(sW + sn * 64), b_n = *(const LAS f32x4*)(sB + sn * 64);
;                             const f32x4 k_n = *(const LAS f32x4*)(sK + sn * 64), r_n = *(const LAS f32x4*)(sR + sn * 64);
;                             const float v = vq[u16 >> 2][u16 & 3];
;                             const f32x2 vv = {v, v};
;                             f32x2 pp = S01 * (f32x2){a_[0], a_[1]}; pp = S23 * (f32x2){a_[2], a_[3]} + pp;
;                             f32x2 yy = S01 * (f32x2){rp[0], rp[1]}; yy = S23 * (f32x2){rp[2], rp[3]} + yy;
;                             float sa = pp[0] + pp[1], y = yy[0] + yy[1];
;                             sa += dpp_f<0xB1>(sa); y += dpp_f<0xB1>(y);
;                             sa += dpp_f<0x4E>(sa); y += dpp_f<0x4E>(y);
;                             sa += dpp_f<0x141>(sa); y += dpp_f<0x141>(y);
;                             sa += dpp_f<0x140>(sa); y += dpp_f<0x140>(y);
;                             sY[((s - 1) & 31) * 16 + srow] = y;
;                             const f32x2 sv = {sa, sa};
;                             S01 = S01 * (f32x2){w_[0], w_[1]} + vv * (f32x2){k_[0], k_[1]};
;                             S23 = S23 * (f32x2){w_[2], w_[3]} + vv * (f32x2){k_[2], k_[3]};
;                             S01 = sv * (f32x2){b_[0], b_[1]} + S01;
;                             S23 = sv * (f32x2){b_[2], b_[3]} + S23;
;                             rp = r_;
;                             a_ = a_n; w_ = w_n; b_ = b_n; k_ = k_n; r_ = r_n;
;                         }
	v_pk_mul_f32 v[228:229], v[166:167], v[100:101]
	v_pk_mul_f32 v[230:231], v[166:167], v[96:97]
	v_pk_fma_f32 v[228:229], v[164:165], v[102:103], v[228:229]
	v_pk_fma_f32 v[230:231], v[164:165], v[98:99], v[230:231]
	v_add_f32_e32 v236, v228, v229
	v_pk_mul_f32 v[232:233], v[220:221], v[112:113] op_sel_hi:[0,1]
	v_add_f32_e32 v237, v230, v231
	v_add_f32_dpp v236, v236, v236 quad_perm:[1,0,3,2] row_mask:0xf bank_mask:0xf bound_ctrl:1
	v_pk_mul_f32 v[234:235], v[220:221], v[114:115] op_sel_hi:[0,1]
	ds_read_b128 v[80:83], v241 offset:32256
	v_add_f32_dpp v236, v236, v236 quad_perm:[2,3,0,1] row_mask:0xf bank_mask:0xf bound_ctrl:1
	v_pk_fma_f32 v[166:167], v[166:167], v[104:105], v[232:233]
	ds_read_b128 v[84:87], v240 offset:50688
	v_add_f32_dpp v236, v236, v236 row_half_mirror row_mask:0xf bank_mask:0xf bound_ctrl:1
	v_pk_fma_f32 v[164:165], v[164:165], v[106:107], v[234:235]
	ds_read_b128 v[92:95], v240 offset:58880
	v_add_f32_dpp v236, v236, v236 row_mirror row_mask:0xf bank_mask:0xf bound_ctrl:1
	v_add_f32_dpp v239, v239, v239 row_mirror row_mask:0xf bank_mask:0xf bound_ctrl:1
	v_add_f32_dpp v239, v250, v250 row_mirror row_mask:0xf bank_mask:0xc bound_ctrl:1
	v_pk_fma_f32 v[166:167], v[108:109], v[236:237], v[166:167] op_sel_hi:[1,0,1]
	v_pk_fma_f32 v[164:165], v[110:111], v[236:237], v[164:165] op_sel_hi:[1,0,1]
	ds_read_b128 v[88:91], v241 offset:40448
	ds_read_b128 v[96:99], v240 offset:42496
	s_waitcnt lgkmcnt(5)
	v_pk_mul_f32 v[228:229], v[166:167], v[120:121]
	v_pk_mul_f32 v[230:231], v[166:167], v[116:117]
	v_pk_fma_f32 v[228:229], v[164:165], v[122:123], v[228:229]
	v_pk_fma_f32 v[230:231], v[164:165], v[118:119], v[230:231]
	v_add_f32_e32 v236, v228, v229
	v_pk_mul_f32 v[232:233], v[220:221], v[208:209] op_sel:[1,0]
	v_add_f32_e32 v245, v230, v231
	v_add_f32_dpp v236, v236, v236 quad_perm:[1,0,3,2] row_mask:0xf bank_mask:0xf bound_ctrl:1
	v_pk_mul_f32 v[234:235], v[220:221], v[210:211] op_sel:[1,0]
	ds_read_b128 v[100:103], v241 offset:32512
	v_add_f32_dpp v236, v236, v236 quad_perm:[2,3,0,1] row_mask:0xf bank_mask:0xf bound_ctrl:1
	v_pk_fma_f32 v[166:167], v[166:167], v[124:125], v[232:233]
	ds_read_b128 v[104:107], v240 offset:50944
	v_add_f32_dpp v236, v236, v236 row_half_mirror row_mask:0xf bank_mask:0xf bound_ctrl:1
	v_pk_fma_f32 v[164:165], v[164:165], v[126:127], v[234:235]
	ds_read_b128 v[112:115], v240 offset:59136
	v_add_f32_dpp v236, v236, v236 row_mirror row_mask:0xf bank_mask:0xf bound_ctrl:1
	v_add_f32_dpp v202, v202, v202 row_mirror row_mask:0xf bank_mask:0xf bound_ctrl:1
	v_add_f32_dpp v202, v251, v251 row_mirror row_mask:0xf bank_mask:0xc bound_ctrl:1
	v_pk_fma_f32 v[166:167], v[204:205], v[236:237], v[166:167] op_sel_hi:[1,0,1]
	v_pk_fma_f32 v[164:165], v[206:207], v[236:237], v[164:165] op_sel_hi:[1,0,1]
	ds_read_b128 v[108:111], v241 offset:40704
	ds_read_b128 v[116:119], v240 offset:42752
	s_waitcnt lgkmcnt(5)
	v_pk_mul_f32 v[228:229], v[166:167], v[80:81]
	v_pk_mul_f32 v[230:231], v[166:167], v[212:213]
	v_pk_fma_f32 v[228:229], v[164:165], v[82:83], v[228:229]
	v_pk_fma_f32 v[230:231], v[164:165], v[214:215], v[230:231]
	v_add_f32_e32 v236, v228, v229
	v_pk_mul_f32 v[232:233], v[222:223], v[92:93] op_sel_hi:[0,1]
	v_add_f32_e32 v246, v230, v231
	v_add_f32_dpp v236, v236, v236 quad_perm:[1,0,3,2] row_mask:0xf bank_mask:0xf bound_ctrl:1
	v_pk_mul_f32 v[234:235], v[222:223], v[94:95] op_sel_hi:[0,1]
	v_add_f32_dpp v203, v203, v203 row_mirror row_mask:0xf bank_mask:0xf bound_ctrl:1
	v_add_f32_dpp v236, v236, v236 quad_perm:[2,3,0,1] row_mask:0xf bank_mask:0xf bound_ctrl:1
	v_pk_fma_f32 v[166:167], v[166:167], v[84:85], v[232:233]
	v_add_f32_dpp v203, v237, v237 row_mirror row_mask:0xf bank_mask:0xc bound_ctrl:1
	v_add_f32_dpp v236, v236, v236 row_half_mirror row_mask:0xf bank_mask:0xf bound_ctrl:1
	v_pk_fma_f32 v[164:165], v[164:165], v[86:87], v[234:235]
	v_add_f32_dpp v128, v128, v128 row_mirror row_mask:0xf bank_mask:0xf bound_ctrl:1
	v_add_f32_dpp v236, v236, v236 row_mirror row_mask:0xf bank_mask:0xf bound_ctrl:1
	v_add_f32_dpp v128, v245, v245 row_mirror row_mask:0xf bank_mask:0xc bound_ctrl:1
	v_add_f32_dpp v129, v129, v129 row_mirror row_mask:0xf bank_mask:0xf bound_ctrl:1
	v_pk_fma_f32 v[166:167], v[88:89], v[236:237], v[166:167] op_sel_hi:[1,0,1]
	v_pk_fma_f32 v[164:165], v[90:91], v[236:237], v[164:165] op_sel_hi:[1,0,1]
	s_waitcnt lgkmcnt(0)
; #define LAS __attribute__((address_space(3)))
; __device__ __forceinline__ void phase_scan(const Params& p, LAS unsigned char* lds) {
;     ...
;                         for (int u16 = 0; u16 < 16; ++u16) {
;                             const int s = 16 * hb + u16;
;                             const int sn = (s + 1) & 31;
;                             const f32x4 a_n = *(const LAS f32x4*)(sA + sn * 64), w_n = *(const LAS f32x4*)(sW + sn * 64), b_n = *(const LAS f32x4*)(sB + sn * 64);
;                             const f32x4 k_n = *(const LAS f32x4*)(sK + sn * 64), r_n = *(const LAS f32x4*)(sR + sn * 64);
;                             const float v = vq[u16 >> 2][u16 & 3];
;                             const f32x2 vv = {v, v};
;                             f32x2 pp = S01 * (f32x2){a_[0], a_[1]}; pp = S23 * (f32x2){a_[2], a_[3]} + pp;
;                             f32x2 yy = S01 * (f32x2){rp[0], rp[1]}; yy = S23 * (f32x2){rp[2], rp[3]} + yy;
;                             float sa = pp[0] + pp[1], y = yy[0] + yy[1];
;                             sa += dpp_f<0xB1>(sa); y += dpp_f<0xB1>(y);
;                             sa += dpp_f<0x4E>(sa); y += dpp_f<0x4E>(y);
;                             sa += dpp_f<0x141>(sa); y += dpp_f<0x141>(y);
;                             sa += dpp_f<0x140>(sa); y += dpp_f<0x140>(y);
;                             sY[((s - 1) & 31) * 16 + srow] = y;
;                             const f32x2 sv = {sa, sa};
;                             S01 = S01 * (f32x2){w_[0], w_[1]} + vv * (f32x2){k_[0], k_[1]};
;                             S23 = S23 * (f32x2){w_[2], w_[3]} + vv * (f32x2){k_[2], k_[3]};
;                             S01 = sv * (f32x2){b_[0], b_[1]} + S01;
;                             S23 = sv * (f32x2){b_[2], b_[3]} + S23;
;                             rp = r_;
;                             a_ = a_n; w_ = w_n; b_ = b_n; k_ = k_n; r_ = r_n;
;                         }
; #pragma unroll
;                         for (int u = 0; u < 4; ++u) vq[u] = vn[u];
;                     }
;                     { f32x2 yy = S01 * (f32x2){rp[0], rp[1]}; yy = S23 * (f32x2){rp[2], rp[3]} + yy; sY[31 * 16 + srow] = red16(yy[0] + yy[1]); }
;                     __builtin_amdgcn_s_setprio(0);
	v_pk_mul_f32 v[228:229], v[166:167], v[100:101]
	v_pk_mul_f32 v[230:231], v[166:167], v[96:97]
	v_pk_fma_f32 v[228:229], v[164:165], v[102:103], v[228:229]
	v_pk_fma_f32 v[230:231], v[164:165], v[98:99], v[230:231]
	v_add_f32_e32 v236, v228, v229
	v_pk_mul_f32 v[232:233], v[222:223], v[112:113] op_sel:[1,0]
	v_add_f32_e32 v247, v230, v231
	v_add_f32_dpp v236, v236, v236 quad_perm:[1,0,3,2] row_mask:0xf bank_mask:0xf bound_ctrl:1
	v_pk_mul_f32 v[234:235], v[222:223], v[114:115] op_sel:[1,0]
	v_add_f32_dpp v129, v246, v246 row_mirror row_mask:0xf bank_mask:0xc bound_ctrl:1
	v_add_f32_dpp v236, v236, v236 quad_perm:[2,3,0,1] row_mask:0xf bank_mask:0xf bound_ctrl:1
	v_pk_fma_f32 v[166:167], v[166:167], v[104:105], v[232:233]
	v_add_f32_dpp v78, v78, v78 row_mirror row_mask:0xf bank_mask:0xf bound_ctrl:1
	v_add_f32_dpp v236, v236, v236 row_half_mirror row_mask:0xf bank_mask:0xf bound_ctrl:1
	v_pk_fma_f32 v[164:165], v[164:165], v[106:107], v[234:235]
	v_add_f32_dpp v78, v247, v247 row_mirror row_mask:0xf bank_mask:0xc bound_ctrl:1
	v_add_f32_dpp v236, v236, v236 row_mirror row_mask:0xf bank_mask:0xf bound_ctrl:1
	s_nop 0
	v_pk_fma_f32 v[166:167], v[108:109], v[236:237], v[166:167] op_sel_hi:[1,0,1]
	v_pk_fma_f32 v[164:165], v[110:111], v[236:237], v[164:165] op_sel_hi:[1,0,1]
	v_pk_mul_f32 v[230:231], v[166:167], v[116:117]
	s_nop 0
	v_pk_fma_f32 v[230:231], v[164:165], v[118:119], v[230:231]
	s_nop 0
	v_add_f32_e32 v248, v230, v231
	s_nop 1
	v_add_f32_dpp v79, v79, v79 row_mirror row_mask:0xf bank_mask:0xf bound_ctrl:1
	v_add_f32_dpp v79, v248, v248 row_mirror row_mask:0xf bank_mask:0xc bound_ctrl:1
	s_nop 1
	v_add_f32_dpp v238, v238, v238 row_half_mirror row_mask:0xf bank_mask:0xf bound_ctrl:1
	v_add_f32_dpp v239, v239, v239 row_half_mirror row_mask:0xf bank_mask:0xf bound_ctrl:1
	v_add_f32_dpp v202, v202, v202 row_half_mirror row_mask:0xf bank_mask:0xf bound_ctrl:1
	v_add_f32_dpp v203, v203, v203 row_half_mirror row_mask:0xf bank_mask:0xf bound_ctrl:1
	v_add_f32_dpp v238, v128, v128 row_half_mirror row_mask:0xf bank_mask:0xa bound_ctrl:1
	v_add_f32_dpp v239, v129, v129 row_half_mirror row_mask:0xf bank_mask:0xa bound_ctrl:1
	v_add_f32_dpp v202, v78, v78 row_half_mirror row_mask:0xf bank_mask:0xa bound_ctrl:1
	v_add_f32_dpp v203, v79, v79 row_half_mirror row_mask:0xf bank_mask:0xa bound_ctrl:1
	v_add_f32_dpp v238, v238, v238 quad_perm:[1,0,3,2] row_mask:0xf bank_mask:0xf bound_ctrl:1
	v_add_f32_dpp v239, v239, v239 quad_perm:[1,0,3,2] row_mask:0xf bank_mask:0xf bound_ctrl:1
	v_add_f32_dpp v202, v202, v202 quad_perm:[1,0,3,2] row_mask:0xf bank_mask:0xf bound_ctrl:1
	v_add_f32_dpp v203, v203, v203 quad_perm:[1,0,3,2] row_mask:0xf bank_mask:0xf bound_ctrl:1
	v_add_f32_dpp v238, v238, v238 quad_perm:[2,3,0,1] row_mask:0xf bank_mask:0xf bound_ctrl:1
	v_add_f32_dpp v239, v239, v239 quad_perm:[2,3,0,1] row_mask:0xf bank_mask:0xf bound_ctrl:1
	v_add_f32_dpp v202, v202, v202 quad_perm:[2,3,0,1] row_mask:0xf bank_mask:0xf bound_ctrl:1
	v_add_f32_dpp v203, v203, v203 quad_perm:[2,3,0,1] row_mask:0xf bank_mask:0xf bound_ctrl:1
	ds_write_b32 v244, v238 offset:1024
	ds_write_b32 v244, v239 offset:1088
	ds_write_b32 v244, v202 offset:1152
	ds_write_b32 v244, v203 offset:1216
	s_setprio 0
	s_branch .LBB0_603
